# speedup vs baseline: 1.1701x; 1.0044x over previous
;   const int tid = tidx, lane = tid & 63, w = tid >> 6;
;   const int wm = w >> 1, wn = w & 1;
;   const int l15 = lane & 15, quad = lane >> 4;
;   constexpr int NB = (TN * 32 * 8) / NT;
;   constexpr int BUFE = (256 + (TN > 4 ? 192 : 128)) * GSTR;
;   u32x4 ra0[4], ra1[4];
;   u32x4 rb0[NB], rb1[NB];
;   const int cr = tid >> 3, ck = tid & 7;
;   const unsigned aoffb = (unsigned)(cr * lda + ck * 8) * 2u;
;   const unsigned boffb = (unsigned)(cr * ldb + ck * 8) * 2u;
.LBB0_578:
	s_andn2_b64 vcc, exec, s[10:11]
	s_cbranch_vccnz .LBB0_588
	v_readlane_b32 s10, v252, 45
	v_readlane_b32 s11, v252, 46
	s_andn2_b64 vcc, exec, s[10:11]
	s_cbranch_vccnz .LBB0_588
	s_waitcnt vmcnt(14)
	v_ashrrev_i32_e32 v10, 1, v150
	s_waitcnt lgkmcnt(0)
	v_and_b32_e32 v8, 15, v150
	v_and_b32_e32 v10, 0xffffffc0, v10
	v_lshlrev_b32_e32 v0, 4, v150
	s_movk_i32 s5, 0xa0
	v_or_b32_e32 v11, v10, v8
	v_ashrrev_i32_e32 v2, 3, v150
	v_and_b32_e32 v3, 0x70, v0
	v_mul_lo_u32 v20, v11, s5
	s_add_i32 s0, 0, 0xf000
	v_lshl_or_b32 v0, v2, 11, v3
	v_add_u32_e32 v9, 0, v3
	v_mul_lo_u32 v2, v2, s5
	v_add_u32_e32 v11, s0, v20
	v_readlane_b32 s0, v254, 12
	v_and_b32_e32 v18, 48, v150
	s_waitcnt vmcnt(13)
	v_and_b32_e32 v12, 0x4f, v150
	v_add_u32_e32 v22, v9, v2
	v_mov_b32_e32 v9, s0
	v_lshrrev_b32_e32 v17, 2, v150
	v_add_u32_e32 v19, 0, v18
	v_add_u32_e32 v14, s0, v18
	v_lshrrev_b32_e32 v23, 3, v150
	v_and_b32_e32 v25, 4, v23
	v_lshlrev_b32_e32 v25, 2, v25
	v_and_or_b32 v25, v23, 35, v25
	v_and_b32_e32 v23, 24, v23
	v_lshrrev_b32_e32 v23, 1, v23
	v_or_b32_e32 v23, v25, v23
	v_mul_u32_u24_e32 v23, 0xa0, v23
	v_add_u32_e32 v23, 0xa000, v23
	v_add_u32_e32 v23, v23, v3
	s_waitcnt vmcnt(11)
	v_mad_u32_u24 v28, v12, s5, v9
	v_and_or_b32 v10, v17, 12, v10
	v_and_b32_e32 v17, 64, v150
	s_movk_i32 s0, 0x110
	v_mul_u32_u24_e32 v21, 0xa0, v12
	v_add_u32_e32 v13, 0xf000, v19
	s_waitcnt vmcnt(8)
	v_add_u32_e32 v15, 0, v20
	v_mad_u32_u24 v16, v12, s5, 0
	v_add_u32_e32 v2, 0x1400, v11
	v_add_u32_e32 v3, 0x1e00, v11
	v_add_u32_e32 v9, 0xa00, v28
	v_add_u32_e32 v11, 0x1400, v28
	v_add_u32_e32 v12, 0x1e00, v28
	v_lshl_add_u32 v17, v17, 1, 0
	v_lshlrev_b32_e32 v8, 1, v8
	v_mul_lo_u32 v10, v10, s0
	v_add_u32_e32 v24, 0x2800, v22
	v_add_u32_e32 v25, 0x2800, v23
	v_add_u32_e32 v26, 0x5000, v22
	v_add_u32_e32 v27, 0x7800, v22
	v_add3_u32 v29, v17, v8, v10
	v_cmp_gt_i32_e64 s[10:11], s36, v150
	s_mov_b32 s0, 0
	v_add_u32_e32 v30, v15, v18
	v_add_u32_e32 v31, v16, v18
	v_add_u32_e32 v32, v13, v20
	v_add_u32_e32 v33, v14, v21
	v_add_u32_e32 v34, v2, v18
	v_add_u32_e32 v35, v3, v18
	v_add_u32_e32 v36, v9, v18
	v_add_u32_e32 v37, v11, v18
	v_add_u32_e32 v38, v12, v18
	v_readlane_b32 s18, v251, 0
	s_branch .LBB0_582

;     ...
;   G_LOAD(ra0, rb0, 0);
;   G_LOAD(ra1, rb1, 64);
;   __syncthreads();
;   G_STORE(ra0, rb0, 0);
;   __syncthreads();
;   G_READ(fa0, fb0, 0, 0);
; #pragma unroll
;   for (int k0 = 0; k0 < K; k0 += 128) {
;     G_READ(fa1, fb1, 0, 32);
;     if (k0 + 128 < K) G_LOAD(ra0, rb0, k0 + 128);
;     __builtin_amdgcn_sched_barrier(0);
;     G_MFMA_ST(fa0, fb0, ra1, rb1, 1);
;     __syncthreads();
;     G_READ(fa0, fb0, 1, 0);
;     __builtin_amdgcn_sched_barrier(0);
;     G_MFMA(fa1, fb1);
.LBB0_585:
	s_ashr_i32 s15, s14, 31
	s_lshl_b64 s[16:17], s[14:15], 19
	s_add_u32 s16, s50, s16
	s_addc_u32 s17, s51, s17
	v_lshl_add_u64 v[2:3], s[16:17], 0, v[0:1]
	s_mov_b32 s5, 0x20000
	s_ashr_i32 s13, s12, 31
	v_add_co_u32_e32 v8, vcc, s5, v2
	s_lshl_b64 s[20:21], s[12:13], 18
	v_readlane_b32 s22, v251, 20
	v_addc_co_u32_e32 v9, vcc, 0, v3, vcc
	s_mov_b32 s13, 0x40000
	v_readlane_b32 s23, v251, 21
	s_add_u32 s20, s22, s20
	global_load_dwordx4 v[40:43], v[2:3], off
	global_load_dwordx4 v[44:47], v[8:9], off
	v_add_co_u32_e32 v10, vcc, s13, v2
	s_addc_u32 s21, s23, s21
	s_nop 0
	v_addc_co_u32_e32 v11, vcc, 0, v3, vcc
	global_load_dwordx4 v[48:51], v[10:11], off
	v_add_co_u32_e32 v12, vcc, s35, v2
	v_lshl_add_u64 v[14:15], s[20:21], 0, v[0:1]
	s_nop 0
	v_addc_co_u32_e32 v13, vcc, 0, v3, vcc
	global_load_dwordx4 v[56:59], v[14:15], off
	global_load_dwordx4 v[52:55], v[12:13], off
	v_add_co_u32_e32 v16, vcc, s5, v14
	v_add_u32_e32 v39, v19, v20
	s_nop 0
	v_addc_co_u32_e32 v17, vcc, 0, v15, vcc
	global_load_dwordx4 v[60:63], v[16:17], off
	global_load_dwordx4 v[64:67], v[2:3], off offset:128
	global_load_dwordx4 v[68:71], v[8:9], off offset:128
	global_load_dwordx4 v[72:75], v[10:11], off offset:128
	global_load_dwordx4 v[76:79], v[14:15], off offset:128
	global_load_dwordx4 v[80:83], v[12:13], off offset:128
	global_load_dwordx4 v[84:87], v[16:17], off offset:128
	s_barrier
	s_waitcnt vmcnt(11)
	ds_write_b128 v22, v[40:43]
	s_waitcnt vmcnt(10)
	ds_write_b128 v22, v[44:47] offset:10240
	s_waitcnt vmcnt(9)
	ds_write_b128 v22, v[48:51] offset:20480
	s_waitcnt vmcnt(8)
	ds_write_b128 v23, v[56:59]
	s_waitcnt vmcnt(7)
	ds_write_b128 v22, v[52:55] offset:30720
	s_waitcnt vmcnt(6)
	ds_write_b128 v25, v[60:63]
	s_waitcnt lgkmcnt(0)
	s_barrier
	global_load_dwordx4 v[42:45], v[2:3], off offset:256
	global_load_dwordx4 v[46:49], v[8:9], off offset:256
	global_load_dwordx4 v[50:53], v[10:11], off offset:256
	global_load_dwordx4 v[54:57], v[12:13], off offset:256
	global_load_dwordx4 v[58:61], v[14:15], off offset:256
	global_load_dwordx4 v[88:91], v[16:17], off offset:256
	v_add_u32_e32 v40, v19, v21
	ds_read_b128 v[92:95], v39
	ds_read_b128 v[96:99], v39 offset:2560
	ds_read_b128 v[100:103], v39 offset:5120
	ds_read_b128 v[104:107], v39 offset:7680
	ds_read_b128 v[108:111], v40 offset:40960
	ds_read_b128 v[112:115], v40 offset:43520
	ds_read_b128 v[116:119], v40 offset:46080
	ds_read_b128 v[120:123], v40 offset:48640
	ds_read_b128 v[124:127], v30 offset:64
	ds_read_b128 v[128:131], v30 offset:2624
	ds_read_b128 v[132:135], v30 offset:5184
	ds_read_b128 v[136:139], v30 offset:7744
	ds_read_b128 v[140:143], v31 offset:41024
	ds_read_b128 v[144:147], v31 offset:43584
	ds_read_b128 v[152:155], v31 offset:46144
	ds_read_b128 v[156:159], v31 offset:48704
	s_waitcnt lgkmcnt(11)
	v_mfma_f32_16x16x32_bf16 v[174:177], v[108:111], v[92:95], 0
	s_waitcnt vmcnt(11)
	ds_write_b128 v22, v[64:67] offset:61440
	s_waitcnt vmcnt(8)
	ds_write_b128 v23, v[76:79] offset:61440
	s_waitcnt lgkmcnt(12)
	v_mfma_f32_16x16x32_bf16 v[178:181], v[112:115], v[92:95], 0
	s_waitcnt lgkmcnt(11)
	v_mfma_f32_16x16x32_bf16 v[182:185], v[116:119], v[92:95], 0
	s_waitcnt lgkmcnt(10)
	v_mfma_f32_16x16x32_bf16 v[62:65], v[120:123], v[92:95], 0
	v_mfma_f32_16x16x32_bf16 v[76:79], v[108:111], v[96:99], 0
	ds_write_b128 v24, v[68:71] offset:61440
	s_waitcnt vmcnt(6)
	ds_write_b128 v25, v[84:87] offset:61440
	v_mfma_f32_16x16x32_bf16 v[92:95], v[112:115], v[96:99], 0
	v_mfma_f32_16x16x32_bf16 v[186:189], v[116:119], v[96:99], 0
	v_mfma_f32_16x16x32_bf16 v[66:69], v[120:123], v[96:99], 0
	v_mfma_f32_16x16x32_bf16 v[84:87], v[108:111], v[100:103], 0
	ds_write_b128 v26, v[72:75] offset:61440
	v_mfma_f32_16x16x32_bf16 v[96:99], v[112:115], v[100:103], 0
	v_mfma_f32_16x16x32_bf16 v[190:193], v[116:119], v[100:103], 0
	v_mfma_f32_16x16x32_bf16 v[70:73], v[120:123], v[100:103], 0
	v_mfma_f32_16x16x32_bf16 v[100:103], v[108:111], v[104:107], 0
	ds_write_b128 v27, v[80:83] offset:61440
	v_mfma_f32_16x16x32_bf16 v[108:111], v[112:115], v[104:107], 0
	v_mfma_f32_16x16x32_bf16 v[112:115], v[116:119], v[104:107], 0
	v_mfma_f32_16x16x32_bf16 v[80:83], v[120:123], v[104:107], 0
	s_waitcnt lgkmcnt(0)
	s_barrier
	ds_read_b128 v[104:107], v39 offset:61440
	ds_read_b128 v[116:119], v39 offset:64000
	ds_read_b128 v[120:123], v32 offset:5120
	ds_read_b128 v[194:197], v32 offset:7680
	ds_read_b128 v[198:201], v33
	ds_read_b128 v[202:205], v33 offset:2560
	ds_read_b128 v[206:209], v33 offset:5120
	ds_read_b128 v[210:213], v33 offset:7680
	v_mfma_f32_16x16x32_bf16 v[174:177], v[140:143], v[124:127], v[174:177]
	v_mfma_f32_16x16x32_bf16 v[178:181], v[144:147], v[124:127], v[178:181]
	v_mfma_f32_16x16x32_bf16 v[182:185], v[152:155], v[124:127], v[182:185]
	v_mfma_f32_16x16x32_bf16 v[62:65], v[156:159], v[124:127], v[62:65]
	v_mfma_f32_16x16x32_bf16 v[74:77], v[140:143], v[128:131], v[76:79]
	v_mfma_f32_16x16x32_bf16 v[92:95], v[144:147], v[128:131], v[92:95]
	v_mfma_f32_16x16x32_bf16 v[124:127], v[152:155], v[128:131], v[186:189]
	v_mfma_f32_16x16x32_bf16 v[66:69], v[156:159], v[128:131], v[66:69]
	v_mfma_f32_16x16x32_bf16 v[84:87], v[140:143], v[132:135], v[84:87]
	v_mfma_f32_16x16x32_bf16 v[96:99], v[144:147], v[132:135], v[96:99]
	v_mfma_f32_16x16x32_bf16 v[128:131], v[152:155], v[132:135], v[190:193]
	v_mfma_f32_16x16x32_bf16 v[70:73], v[156:159], v[132:135], v[70:73]
	v_mfma_f32_16x16x32_bf16 v[100:103], v[140:143], v[136:139], v[100:103]
	v_mfma_f32_16x16x32_bf16 v[108:111], v[144:147], v[136:139], v[108:111]
	v_mfma_f32_16x16x32_bf16 v[112:115], v[152:155], v[136:139], v[112:115]
	v_mfma_f32_16x16x32_bf16 v[78:81], v[156:159], v[136:139], v[80:83]
	global_load_dwordx4 v[132:135], v[2:3], off offset:384
	global_load_dwordx4 v[136:139], v[8:9], off offset:384
	global_load_dwordx4 v[140:143], v[10:11], off offset:384
	global_load_dwordx4 v[144:147], v[12:13], off offset:384
	global_load_dwordx4 v[152:155], v[14:15], off offset:384
	global_load_dwordx4 v[156:159], v[16:17], off offset:384
	v_add_u32_e32 v41, v28, v18
	ds_read_b128 v[186:189], v30 offset:61504
	ds_read_b128 v[190:193], v30 offset:64064
	ds_read_b128 v[214:217], v34 offset:64
	ds_read_b128 v[218:221], v35 offset:64
	ds_read_b128 v[222:225], v41 offset:64
	ds_read_b128 v[226:229], v36 offset:64
	ds_read_b128 v[230:233], v37 offset:64
	ds_read_b128 v[234:237], v38 offset:64
	s_waitcnt lgkmcnt(11)
;     ...
;   for (int k0 = 0; k0 < K; k0 += 128) {
;     G_READ(fa1, fb1, 0, 32);
;     if (k0 + 128 < K) G_LOAD(ra0, rb0, k0 + 128);
;     __builtin_amdgcn_sched_barrier(0);
;     G_MFMA_ST(fa0, fb0, ra1, rb1, 1);
;     __syncthreads();
;     G_READ(fa0, fb0, 1, 0);
;     __builtin_amdgcn_sched_barrier(0);
;     G_MFMA(fa1, fb1);
;     __builtin_amdgcn_sched_barrier(0);
;     G_READ(fa1, fb1, 1, 32);
;     if (k0 + 192 < K) G_LOAD(ra1, rb1, k0 + 192);
;     __builtin_amdgcn_sched_barrier(0);
;     if (k0 + 128 < K) {
;       G_MFMA_ST(fa0, fb0, ra0, rb0, 0);
;       __syncthreads();
;       G_READ(fa0, fb0, 0, 0);
;     } else {
;       G_MFMA(fa0, fb0);
;     }
;     __builtin_amdgcn_sched_barrier(0);
;     G_MFMA(fa1, fb1);
;     __builtin_amdgcn_sched_barrier(0);
;   }
	v_mfma_f32_16x16x32_bf16 v[174:177], v[198:201], v[104:107], v[174:177]
	s_waitcnt vmcnt(11)
	ds_write_b128 v22, v[42:45]
	s_waitcnt vmcnt(7)
	ds_write_b128 v23, v[58:61]
	s_waitcnt lgkmcnt(12)
	v_mfma_f32_16x16x32_bf16 v[178:181], v[202:205], v[104:107], v[178:181]
	s_waitcnt lgkmcnt(11)
	v_mfma_f32_16x16x32_bf16 v[182:185], v[206:209], v[104:107], v[182:185]
	s_waitcnt lgkmcnt(10)
	v_mfma_f32_16x16x32_bf16 v[42:45], v[210:213], v[104:107], v[62:65]
	v_mfma_f32_16x16x32_bf16 v[58:61], v[198:201], v[116:119], v[74:77]
	ds_write_b128 v22, v[46:49] offset:10240
	s_waitcnt vmcnt(6)
	ds_write_b128 v25, v[88:91]
	v_mfma_f32_16x16x32_bf16 v[62:65], v[202:205], v[116:119], v[92:95]
	v_mfma_f32_16x16x32_bf16 v[74:77], v[206:209], v[116:119], v[124:127]
	v_mfma_f32_16x16x32_bf16 v[46:49], v[210:213], v[116:119], v[66:69]
	v_mfma_f32_16x16x32_bf16 v[66:69], v[198:201], v[120:123], v[84:87]
	ds_write_b128 v22, v[50:53] offset:20480
	v_mfma_f32_16x16x32_bf16 v[82:85], v[202:205], v[120:123], v[96:99]
	v_mfma_f32_16x16x32_bf16 v[86:89], v[206:209], v[120:123], v[128:131]
	v_mfma_f32_16x16x32_bf16 v[50:53], v[210:213], v[120:123], v[70:73]
	v_mfma_f32_16x16x32_bf16 v[70:73], v[198:201], v[194:197], v[100:103]
	ds_write_b128 v22, v[54:57] offset:30720
	v_mfma_f32_16x16x32_bf16 v[90:93], v[202:205], v[194:197], v[108:111]
	v_mfma_f32_16x16x32_bf16 v[94:97], v[206:209], v[194:197], v[112:115]
	v_mfma_f32_16x16x32_bf16 v[54:57], v[210:213], v[194:197], v[78:81]
	s_waitcnt lgkmcnt(0)
	s_barrier
	s_nop 0
	ds_read_b128 v[78:81], v39
	ds_read_b128 v[98:101], v39 offset:2560
	ds_read_b128 v[102:105], v39 offset:5120
	ds_read_b128 v[106:109], v39 offset:7680
	ds_read_b128 v[110:113], v40 offset:40960
	ds_read_b128 v[114:117], v40 offset:43520
	ds_read_b128 v[118:121], v40 offset:46080
	ds_read_b128 v[122:125], v40 offset:48640
	v_mfma_f32_16x16x32_bf16 v[126:129], v[222:225], v[186:189], v[174:177]
	v_mfma_f32_16x16x32_bf16 v[174:177], v[226:229], v[186:189], v[178:181]
	v_mfma_f32_16x16x32_bf16 v[178:181], v[230:233], v[186:189], v[182:185]
	v_mfma_f32_16x16x32_bf16 v[42:45], v[234:237], v[186:189], v[42:45]
	v_mfma_f32_16x16x32_bf16 v[58:61], v[222:225], v[190:193], v[58:61]
	v_mfma_f32_16x16x32_bf16 v[62:65], v[226:229], v[190:193], v[62:65]
	v_mfma_f32_16x16x32_bf16 v[74:77], v[230:233], v[190:193], v[74:77]
	v_mfma_f32_16x16x32_bf16 v[46:49], v[234:237], v[190:193], v[46:49]
	v_mfma_f32_16x16x32_bf16 v[66:69], v[222:225], v[214:217], v[66:69]
	v_mfma_f32_16x16x32_bf16 v[82:85], v[226:229], v[214:217], v[82:85]
	v_mfma_f32_16x16x32_bf16 v[86:89], v[230:233], v[214:217], v[86:89]
	v_mfma_f32_16x16x32_bf16 v[50:53], v[234:237], v[214:217], v[50:53]
	v_mfma_f32_16x16x32_bf16 v[70:73], v[222:225], v[218:221], v[70:73]
	v_mfma_f32_16x16x32_bf16 v[90:93], v[226:229], v[218:221], v[90:93]
	v_mfma_f32_16x16x32_bf16 v[94:97], v[230:233], v[218:221], v[94:97]
	v_mfma_f32_16x16x32_bf16 v[54:57], v[234:237], v[218:221], v[54:57]
	global_load_dwordx4 v[182:185], v[2:3], off offset:512
	global_load_dwordx4 v[186:189], v[8:9], off offset:512
	global_load_dwordx4 v[190:193], v[10:11], off offset:512
	global_load_dwordx4 v[194:197], v[12:13], off offset:512
	global_load_dwordx4 v[198:201], v[14:15], off offset:512
	global_load_dwordx4 v[202:205], v[16:17], off offset:512
	ds_read_b128 v[206:209], v30 offset:64
	ds_read_b128 v[210:213], v30 offset:2624
	ds_read_b128 v[214:217], v30 offset:5184
	ds_read_b128 v[218:221], v30 offset:7744
	ds_read_b128 v[222:225], v31 offset:41024
	ds_read_b128 v[226:229], v31 offset:43584
	ds_read_b128 v[230:233], v31 offset:46144
	ds_read_b128 v[234:237], v31 offset:48704
	s_waitcnt lgkmcnt(11)
	v_mfma_f32_16x16x32_bf16 v[126:129], v[110:113], v[78:81], v[126:129]
	s_waitcnt vmcnt(11)
	ds_write_b128 v22, v[132:135] offset:61440
	s_waitcnt vmcnt(7)
	ds_write_b128 v23, v[152:155] offset:61440
	s_waitcnt lgkmcnt(12)
	v_mfma_f32_16x16x32_bf16 v[174:177], v[114:117], v[78:81], v[174:177]
	s_waitcnt lgkmcnt(11)
	v_mfma_f32_16x16x32_bf16 v[178:181], v[118:121], v[78:81], v[178:181]
	s_waitcnt lgkmcnt(10)
	v_mfma_f32_16x16x32_bf16 v[42:45], v[122:125], v[78:81], v[42:45]
	v_mfma_f32_16x16x32_bf16 v[58:61], v[110:113], v[98:101], v[58:61]
	ds_write_b128 v24, v[136:139] offset:61440
	s_waitcnt vmcnt(6)
	ds_write_b128 v25, v[156:159] offset:61440
	v_mfma_f32_16x16x32_bf16 v[62:65], v[114:117], v[98:101], v[62:65]
	v_mfma_f32_16x16x32_bf16 v[74:77], v[118:121], v[98:101], v[74:77]
	v_mfma_f32_16x16x32_bf16 v[46:49], v[122:125], v[98:101], v[46:49]
	v_mfma_f32_16x16x32_bf16 v[66:69], v[110:113], v[102:105], v[66:69]
	ds_write_b128 v26, v[140:143] offset:61440
	v_mfma_f32_16x16x32_bf16 v[78:81], v[114:117], v[102:105], v[82:85]
	v_mfma_f32_16x16x32_bf16 v[82:85], v[118:121], v[102:105], v[86:89]
	v_mfma_f32_16x16x32_bf16 v[50:53], v[122:125], v[102:105], v[50:53]
	v_mfma_f32_16x16x32_bf16 v[70:73], v[110:113], v[106:109], v[70:73]
	ds_write_b128 v27, v[144:147] offset:61440
	v_mfma_f32_16x16x32_bf16 v[86:89], v[114:117], v[106:109], v[90:93]
	v_mfma_f32_16x16x32_bf16 v[90:93], v[118:121], v[106:109], v[94:97]
	v_mfma_f32_16x16x32_bf16 v[54:57], v[122:125], v[106:109], v[54:57]
	s_waitcnt lgkmcnt(0)
	s_barrier
;     ...
;   for (int k0 = 0; k0 < K; k0 += 128) {
;     G_READ(fa1, fb1, 0, 32);
;     if (k0 + 128 < K) G_LOAD(ra0, rb0, k0 + 128);
;     __builtin_amdgcn_sched_barrier(0);
;     G_MFMA_ST(fa0, fb0, ra1, rb1, 1);
;     __syncthreads();
;     G_READ(fa0, fb0, 1, 0);
;     __builtin_amdgcn_sched_barrier(0);
;     G_MFMA(fa1, fb1);
;     __builtin_amdgcn_sched_barrier(0);
;     G_READ(fa1, fb1, 1, 32);
;     if (k0 + 192 < K) G_LOAD(ra1, rb1, k0 + 192);
;     __builtin_amdgcn_sched_barrier(0);
;     if (k0 + 128 < K) {
;       G_MFMA_ST(fa0, fb0, ra0, rb0, 0);
;       __syncthreads();
;       G_READ(fa0, fb0, 0, 0);
;     } else {
;       G_MFMA(fa0, fb0);
;     }
;     __builtin_amdgcn_sched_barrier(0);
;     G_MFMA(fa1, fb1);
;     __builtin_amdgcn_sched_barrier(0);
;   }
	ds_read_b128 v[94:97], v39 offset:61440
	ds_read_b128 v[98:101], v39 offset:64000
	ds_read_b128 v[102:105], v32 offset:5120
	ds_read_b128 v[106:109], v32 offset:7680
	ds_read_b128 v[110:113], v33
	ds_read_b128 v[114:117], v33 offset:2560
	ds_read_b128 v[118:121], v33 offset:5120
	ds_read_b128 v[122:125], v33 offset:7680
	v_mfma_f32_16x16x32_bf16 v[126:129], v[222:225], v[206:209], v[126:129]
	v_mfma_f32_16x16x32_bf16 v[130:133], v[226:229], v[206:209], v[174:177]
	v_mfma_f32_16x16x32_bf16 v[134:137], v[230:233], v[206:209], v[178:181]
	v_mfma_f32_16x16x32_bf16 v[42:45], v[234:237], v[206:209], v[42:45]
	v_mfma_f32_16x16x32_bf16 v[58:61], v[222:225], v[210:213], v[58:61]
	v_mfma_f32_16x16x32_bf16 v[62:65], v[226:229], v[210:213], v[62:65]
	v_mfma_f32_16x16x32_bf16 v[74:77], v[230:233], v[210:213], v[74:77]
	v_mfma_f32_16x16x32_bf16 v[46:49], v[234:237], v[210:213], v[46:49]
	v_mfma_f32_16x16x32_bf16 v[66:69], v[222:225], v[214:217], v[66:69]
	v_mfma_f32_16x16x32_bf16 v[78:81], v[226:229], v[214:217], v[78:81]
	v_mfma_f32_16x16x32_bf16 v[82:85], v[230:233], v[214:217], v[82:85]
	v_mfma_f32_16x16x32_bf16 v[50:53], v[234:237], v[214:217], v[50:53]
	v_mfma_f32_16x16x32_bf16 v[70:73], v[222:225], v[218:221], v[70:73]
	v_mfma_f32_16x16x32_bf16 v[86:89], v[226:229], v[218:221], v[86:89]
	v_mfma_f32_16x16x32_bf16 v[90:93], v[230:233], v[218:221], v[90:93]
	v_mfma_f32_16x16x32_bf16 v[54:57], v[234:237], v[218:221], v[54:57]
	global_load_dwordx4 v[138:141], v[2:3], off offset:640
	global_load_dwordx4 v[142:145], v[8:9], off offset:640
	global_load_dwordx4 v[152:155], v[10:11], off offset:640
	global_load_dwordx4 v[156:159], v[12:13], off offset:640
	global_load_dwordx4 v[174:177], v[14:15], off offset:640
	global_load_dwordx4 v[178:181], v[16:17], off offset:640
	ds_read_b128 v[206:209], v30 offset:61504
	ds_read_b128 v[210:213], v30 offset:64064
	ds_read_b128 v[214:217], v34 offset:64
	ds_read_b128 v[218:221], v35 offset:64
	ds_read_b128 v[222:225], v41 offset:64
	ds_read_b128 v[226:229], v36 offset:64
	ds_read_b128 v[230:233], v37 offset:64
	ds_read_b128 v[234:237], v38 offset:64
	s_waitcnt lgkmcnt(11)
	v_mfma_f32_16x16x32_bf16 v[126:129], v[110:113], v[94:97], v[126:129]
	s_waitcnt vmcnt(11)
	ds_write_b128 v22, v[182:185]
	s_waitcnt vmcnt(7)
	ds_write_b128 v23, v[198:201]
	s_waitcnt lgkmcnt(12)
	v_mfma_f32_16x16x32_bf16 v[130:133], v[114:117], v[94:97], v[130:133]
	s_waitcnt lgkmcnt(11)
	v_mfma_f32_16x16x32_bf16 v[134:137], v[118:121], v[94:97], v[134:137]
	s_waitcnt lgkmcnt(10)
	v_mfma_f32_16x16x32_bf16 v[42:45], v[122:125], v[94:97], v[42:45]
	v_mfma_f32_16x16x32_bf16 v[58:61], v[110:113], v[98:101], v[58:61]
	ds_write_b128 v22, v[186:189] offset:10240
	s_waitcnt vmcnt(6)
	ds_write_b128 v25, v[202:205]
	v_mfma_f32_16x16x32_bf16 v[62:65], v[114:117], v[98:101], v[62:65]
	v_mfma_f32_16x16x32_bf16 v[74:77], v[118:121], v[98:101], v[74:77]
	v_mfma_f32_16x16x32_bf16 v[46:49], v[122:125], v[98:101], v[46:49]
	v_mfma_f32_16x16x32_bf16 v[66:69], v[110:113], v[102:105], v[66:69]
	ds_write_b128 v22, v[190:193] offset:20480
	v_mfma_f32_16x16x32_bf16 v[78:81], v[114:117], v[102:105], v[78:81]
	v_mfma_f32_16x16x32_bf16 v[82:85], v[118:121], v[102:105], v[82:85]
	v_mfma_f32_16x16x32_bf16 v[50:53], v[122:125], v[102:105], v[50:53]
	v_mfma_f32_16x16x32_bf16 v[70:73], v[110:113], v[106:109], v[70:73]
	ds_write_b128 v22, v[194:197] offset:30720
	v_mfma_f32_16x16x32_bf16 v[86:89], v[114:117], v[106:109], v[86:89]
	v_mfma_f32_16x16x32_bf16 v[90:93], v[118:121], v[106:109], v[90:93]
	v_mfma_f32_16x16x32_bf16 v[54:57], v[122:125], v[106:109], v[54:57]
	s_waitcnt lgkmcnt(0)
	s_barrier
	ds_read_b128 v[94:97], v39
	ds_read_b128 v[98:101], v39 offset:2560
	ds_read_b128 v[102:105], v39 offset:5120
	ds_read_b128 v[106:109], v39 offset:7680
	ds_read_b128 v[110:113], v40 offset:40960
	ds_read_b128 v[114:117], v40 offset:43520
	ds_read_b128 v[118:121], v40 offset:46080
	ds_read_b128 v[122:125], v40 offset:48640
	v_mfma_f32_16x16x32_bf16 v[126:129], v[222:225], v[206:209], v[126:129]
	v_mfma_f32_16x16x32_bf16 v[130:133], v[226:229], v[206:209], v[130:133]
	v_mfma_f32_16x16x32_bf16 v[134:137], v[230:233], v[206:209], v[134:137]
	v_mfma_f32_16x16x32_bf16 v[42:45], v[234:237], v[206:209], v[42:45]
	v_mfma_f32_16x16x32_bf16 v[58:61], v[222:225], v[210:213], v[58:61]
	v_mfma_f32_16x16x32_bf16 v[62:65], v[226:229], v[210:213], v[62:65]
	v_mfma_f32_16x16x32_bf16 v[74:77], v[230:233], v[210:213], v[74:77]
	v_mfma_f32_16x16x32_bf16 v[46:49], v[234:237], v[210:213], v[46:49]
	v_mfma_f32_16x16x32_bf16 v[66:69], v[222:225], v[214:217], v[66:69]
	v_mfma_f32_16x16x32_bf16 v[78:81], v[226:229], v[214:217], v[78:81]
	v_mfma_f32_16x16x32_bf16 v[82:85], v[230:233], v[214:217], v[82:85]
	v_mfma_f32_16x16x32_bf16 v[50:53], v[234:237], v[214:217], v[50:53]
	v_mfma_f32_16x16x32_bf16 v[70:73], v[222:225], v[218:221], v[70:73]
	v_mfma_f32_16x16x32_bf16 v[86:89], v[226:229], v[218:221], v[86:89]
	v_mfma_f32_16x16x32_bf16 v[90:93], v[230:233], v[218:221], v[90:93]
	v_mfma_f32_16x16x32_bf16 v[54:57], v[234:237], v[218:221], v[54:57]
	global_load_dwordx4 v[182:185], v[2:3], off offset:768
	global_load_dwordx4 v[186:189], v[8:9], off offset:768
	global_load_dwordx4 v[190:193], v[10:11], off offset:768
	global_load_dwordx4 v[194:197], v[12:13], off offset:768
	global_load_dwordx4 v[198:201], v[14:15], off offset:768
	global_load_dwordx4 v[202:205], v[16:17], off offset:768
	ds_read_b128 v[206:209], v30 offset:64
	ds_read_b128 v[210:213], v30 offset:2624
	ds_read_b128 v[214:217], v30 offset:5184
	ds_read_b128 v[218:221], v30 offset:7744
	ds_read_b128 v[222:225], v31 offset:41024
	ds_read_b128 v[226:229], v31 offset:43584
	ds_read_b128 v[230:233], v31 offset:46144
	ds_read_b128 v[234:237], v31 offset:48704
	s_waitcnt lgkmcnt(11)
;     ...
;   for (int k0 = 0; k0 < K; k0 += 128) {
;     G_READ(fa1, fb1, 0, 32);
;     if (k0 + 128 < K) G_LOAD(ra0, rb0, k0 + 128);
;     __builtin_amdgcn_sched_barrier(0);
;     G_MFMA_ST(fa0, fb0, ra1, rb1, 1);
;     __syncthreads();
;     G_READ(fa0, fb0, 1, 0);
;     __builtin_amdgcn_sched_barrier(0);
;     G_MFMA(fa1, fb1);
;     __builtin_amdgcn_sched_barrier(0);
;     G_READ(fa1, fb1, 1, 32);
;     if (k0 + 192 < K) G_LOAD(ra1, rb1, k0 + 192);
;     __builtin_amdgcn_sched_barrier(0);
;     if (k0 + 128 < K) {
;       G_MFMA_ST(fa0, fb0, ra0, rb0, 0);
;       __syncthreads();
;       G_READ(fa0, fb0, 0, 0);
;     } else {
;       G_MFMA(fa0, fb0);
;     }
;     __builtin_amdgcn_sched_barrier(0);
;     G_MFMA(fa1, fb1);
;     __builtin_amdgcn_sched_barrier(0);
;   }
	v_mfma_f32_16x16x32_bf16 v[126:129], v[110:113], v[94:97], v[126:129]
	s_waitcnt vmcnt(11)
	ds_write_b128 v22, v[138:141] offset:61440
	s_waitcnt vmcnt(7)
	ds_write_b128 v23, v[174:177] offset:61440
	s_waitcnt lgkmcnt(12)
	v_mfma_f32_16x16x32_bf16 v[130:133], v[114:117], v[94:97], v[130:133]
	s_waitcnt lgkmcnt(11)
	v_mfma_f32_16x16x32_bf16 v[134:137], v[118:121], v[94:97], v[134:137]
	s_waitcnt lgkmcnt(10)
	v_mfma_f32_16x16x32_bf16 v[42:45], v[122:125], v[94:97], v[42:45]
	v_mfma_f32_16x16x32_bf16 v[58:61], v[110:113], v[98:101], v[58:61]
	ds_write_b128 v24, v[142:145] offset:61440
	s_waitcnt vmcnt(6)
	ds_write_b128 v25, v[178:181] offset:61440
	v_mfma_f32_16x16x32_bf16 v[62:65], v[114:117], v[98:101], v[62:65]
	v_mfma_f32_16x16x32_bf16 v[74:77], v[118:121], v[98:101], v[74:77]
	v_mfma_f32_16x16x32_bf16 v[46:49], v[122:125], v[98:101], v[46:49]
	v_mfma_f32_16x16x32_bf16 v[66:69], v[110:113], v[102:105], v[66:69]
	ds_write_b128 v26, v[152:155] offset:61440
	v_mfma_f32_16x16x32_bf16 v[78:81], v[114:117], v[102:105], v[78:81]
	v_mfma_f32_16x16x32_bf16 v[82:85], v[118:121], v[102:105], v[82:85]
	v_mfma_f32_16x16x32_bf16 v[50:53], v[122:125], v[102:105], v[50:53]
	v_mfma_f32_16x16x32_bf16 v[70:73], v[110:113], v[106:109], v[70:73]
	ds_write_b128 v27, v[156:159] offset:61440
	v_mfma_f32_16x16x32_bf16 v[86:89], v[114:117], v[106:109], v[86:89]
	v_mfma_f32_16x16x32_bf16 v[90:93], v[118:121], v[106:109], v[90:93]
	v_mfma_f32_16x16x32_bf16 v[54:57], v[122:125], v[106:109], v[54:57]
	s_waitcnt lgkmcnt(0)
	s_barrier
	ds_read_b128 v[94:97], v39 offset:61440
	ds_read_b128 v[98:101], v39 offset:64000
	ds_read_b128 v[102:105], v32 offset:5120
	ds_read_b128 v[106:109], v32 offset:7680
	ds_read_b128 v[110:113], v33
	ds_read_b128 v[114:117], v33 offset:2560
	ds_read_b128 v[118:121], v33 offset:5120
	ds_read_b128 v[122:125], v33 offset:7680
	v_mfma_f32_16x16x32_bf16 v[126:129], v[222:225], v[206:209], v[126:129]
	v_mfma_f32_16x16x32_bf16 v[130:133], v[226:229], v[206:209], v[130:133]
	v_mfma_f32_16x16x32_bf16 v[134:137], v[230:233], v[206:209], v[134:137]
	v_mfma_f32_16x16x32_bf16 v[42:45], v[234:237], v[206:209], v[42:45]
	v_mfma_f32_16x16x32_bf16 v[58:61], v[222:225], v[210:213], v[58:61]
	v_mfma_f32_16x16x32_bf16 v[62:65], v[226:229], v[210:213], v[62:65]
	v_mfma_f32_16x16x32_bf16 v[74:77], v[230:233], v[210:213], v[74:77]
	v_mfma_f32_16x16x32_bf16 v[46:49], v[234:237], v[210:213], v[46:49]
	v_mfma_f32_16x16x32_bf16 v[66:69], v[222:225], v[214:217], v[66:69]
	v_mfma_f32_16x16x32_bf16 v[78:81], v[226:229], v[214:217], v[78:81]
	v_mfma_f32_16x16x32_bf16 v[82:85], v[230:233], v[214:217], v[82:85]
	v_mfma_f32_16x16x32_bf16 v[50:53], v[234:237], v[214:217], v[50:53]
	v_mfma_f32_16x16x32_bf16 v[70:73], v[222:225], v[218:221], v[70:73]
	v_mfma_f32_16x16x32_bf16 v[86:89], v[226:229], v[218:221], v[86:89]
	v_mfma_f32_16x16x32_bf16 v[90:93], v[230:233], v[218:221], v[90:93]
	v_mfma_f32_16x16x32_bf16 v[54:57], v[234:237], v[218:221], v[54:57]
	global_load_dwordx4 v[138:141], v[2:3], off offset:896
	global_load_dwordx4 v[142:145], v[8:9], off offset:896
	global_load_dwordx4 v[152:155], v[10:11], off offset:896
	global_load_dwordx4 v[156:159], v[12:13], off offset:896
	global_load_dwordx4 v[174:177], v[14:15], off offset:896
	global_load_dwordx4 v[178:181], v[16:17], off offset:896
	ds_read_b128 v[206:209], v30 offset:61504
	ds_read_b128 v[210:213], v30 offset:64064
	ds_read_b128 v[214:217], v34 offset:64
	ds_read_b128 v[218:221], v35 offset:64
	ds_read_b128 v[222:225], v41 offset:64
	ds_read_b128 v[226:229], v36 offset:64
	ds_read_b128 v[230:233], v37 offset:64
	ds_read_b128 v[234:237], v38 offset:64
	s_waitcnt lgkmcnt(11)
	v_mfma_f32_16x16x32_bf16 v[126:129], v[110:113], v[94:97], v[126:129]
	s_waitcnt vmcnt(11)
	ds_write_b128 v22, v[182:185]
	s_waitcnt vmcnt(7)
	ds_write_b128 v23, v[198:201]
	s_waitcnt lgkmcnt(12)
	v_mfma_f32_16x16x32_bf16 v[130:133], v[114:117], v[94:97], v[130:133]
	s_waitcnt lgkmcnt(11)
	v_mfma_f32_16x16x32_bf16 v[134:137], v[118:121], v[94:97], v[134:137]
	s_waitcnt lgkmcnt(10)
	v_mfma_f32_16x16x32_bf16 v[42:45], v[122:125], v[94:97], v[42:45]
	v_mfma_f32_16x16x32_bf16 v[58:61], v[110:113], v[98:101], v[58:61]
	ds_write_b128 v22, v[186:189] offset:10240
	s_waitcnt vmcnt(6)
	ds_write_b128 v25, v[202:205]
	v_mfma_f32_16x16x32_bf16 v[62:65], v[114:117], v[98:101], v[62:65]
	v_mfma_f32_16x16x32_bf16 v[74:77], v[118:121], v[98:101], v[74:77]
	v_mfma_f32_16x16x32_bf16 v[46:49], v[122:125], v[98:101], v[46:49]
	v_mfma_f32_16x16x32_bf16 v[66:69], v[110:113], v[102:105], v[66:69]
	ds_write_b128 v22, v[190:193] offset:20480
	v_mfma_f32_16x16x32_bf16 v[78:81], v[114:117], v[102:105], v[78:81]
	v_mfma_f32_16x16x32_bf16 v[82:85], v[118:121], v[102:105], v[82:85]
	v_mfma_f32_16x16x32_bf16 v[50:53], v[122:125], v[102:105], v[50:53]
	v_mfma_f32_16x16x32_bf16 v[70:73], v[110:113], v[106:109], v[70:73]
	ds_write_b128 v22, v[194:197] offset:30720
	v_mfma_f32_16x16x32_bf16 v[86:89], v[114:117], v[106:109], v[86:89]
	v_mfma_f32_16x16x32_bf16 v[90:93], v[118:121], v[106:109], v[90:93]
	v_mfma_f32_16x16x32_bf16 v[54:57], v[122:125], v[106:109], v[54:57]
	s_waitcnt lgkmcnt(0)
	s_barrier
;     ...
;   for (int k0 = 0; k0 < K; k0 += 128) {
;     G_READ(fa1, fb1, 0, 32);
;     if (k0 + 128 < K) G_LOAD(ra0, rb0, k0 + 128);
;     __builtin_amdgcn_sched_barrier(0);
;     G_MFMA_ST(fa0, fb0, ra1, rb1, 1);
;     __syncthreads();
;     G_READ(fa0, fb0, 1, 0);
;     __builtin_amdgcn_sched_barrier(0);
;     G_MFMA(fa1, fb1);
;     __builtin_amdgcn_sched_barrier(0);
;     G_READ(fa1, fb1, 1, 32);
;     if (k0 + 192 < K) G_LOAD(ra1, rb1, k0 + 192);
;     __builtin_amdgcn_sched_barrier(0);
;     if (k0 + 128 < K) {
;       G_MFMA_ST(fa0, fb0, ra0, rb0, 0);
;       __syncthreads();
;       G_READ(fa0, fb0, 0, 0);
;     } else {
;       G_MFMA(fa0, fb0);
;     }
;     __builtin_amdgcn_sched_barrier(0);
;     G_MFMA(fa1, fb1);
;     __builtin_amdgcn_sched_barrier(0);
;   }
	ds_read_b128 v[94:97], v39
	ds_read_b128 v[98:101], v39 offset:2560
	ds_read_b128 v[102:105], v39 offset:5120
	ds_read_b128 v[106:109], v39 offset:7680
	ds_read_b128 v[110:113], v40 offset:40960
	ds_read_b128 v[114:117], v40 offset:43520
	ds_read_b128 v[118:121], v40 offset:46080
	ds_read_b128 v[122:125], v40 offset:48640
	v_mfma_f32_16x16x32_bf16 v[126:129], v[222:225], v[206:209], v[126:129]
	v_mfma_f32_16x16x32_bf16 v[130:133], v[226:229], v[206:209], v[130:133]
	v_mfma_f32_16x16x32_bf16 v[134:137], v[230:233], v[206:209], v[134:137]
	v_mfma_f32_16x16x32_bf16 v[42:45], v[234:237], v[206:209], v[42:45]
	v_mfma_f32_16x16x32_bf16 v[58:61], v[222:225], v[210:213], v[58:61]
	v_mfma_f32_16x16x32_bf16 v[62:65], v[226:229], v[210:213], v[62:65]
	v_mfma_f32_16x16x32_bf16 v[74:77], v[230:233], v[210:213], v[74:77]
	v_mfma_f32_16x16x32_bf16 v[46:49], v[234:237], v[210:213], v[46:49]
	v_mfma_f32_16x16x32_bf16 v[66:69], v[222:225], v[214:217], v[66:69]
	v_mfma_f32_16x16x32_bf16 v[78:81], v[226:229], v[214:217], v[78:81]
	v_mfma_f32_16x16x32_bf16 v[82:85], v[230:233], v[214:217], v[82:85]
	v_mfma_f32_16x16x32_bf16 v[50:53], v[234:237], v[214:217], v[50:53]
	v_mfma_f32_16x16x32_bf16 v[70:73], v[222:225], v[218:221], v[70:73]
	v_mfma_f32_16x16x32_bf16 v[86:89], v[226:229], v[218:221], v[86:89]
	v_mfma_f32_16x16x32_bf16 v[90:93], v[230:233], v[218:221], v[90:93]
	v_mfma_f32_16x16x32_bf16 v[54:57], v[234:237], v[218:221], v[54:57]
	global_load_dwordx4 v[182:185], v[2:3], off offset:1024
	global_load_dwordx4 v[186:189], v[8:9], off offset:1024
	global_load_dwordx4 v[190:193], v[10:11], off offset:1024
	global_load_dwordx4 v[194:197], v[12:13], off offset:1024
	global_load_dwordx4 v[198:201], v[14:15], off offset:1024
	global_load_dwordx4 v[202:205], v[16:17], off offset:1024
	ds_read_b128 v[206:209], v30 offset:64
	ds_read_b128 v[210:213], v30 offset:2624
	ds_read_b128 v[214:217], v30 offset:5184
	ds_read_b128 v[218:221], v30 offset:7744
	ds_read_b128 v[222:225], v31 offset:41024
	ds_read_b128 v[226:229], v31 offset:43584
	ds_read_b128 v[230:233], v31 offset:46144
	ds_read_b128 v[234:237], v31 offset:48704
	s_waitcnt lgkmcnt(11)
	v_mfma_f32_16x16x32_bf16 v[126:129], v[110:113], v[94:97], v[126:129]
	s_waitcnt vmcnt(11)
	ds_write_b128 v22, v[138:141] offset:61440
	s_waitcnt vmcnt(7)
	ds_write_b128 v23, v[174:177] offset:61440
	s_waitcnt lgkmcnt(12)
	v_mfma_f32_16x16x32_bf16 v[130:133], v[114:117], v[94:97], v[130:133]
	s_waitcnt lgkmcnt(11)
	v_mfma_f32_16x16x32_bf16 v[134:137], v[118:121], v[94:97], v[134:137]
	s_waitcnt lgkmcnt(10)
	v_mfma_f32_16x16x32_bf16 v[42:45], v[122:125], v[94:97], v[42:45]
	v_mfma_f32_16x16x32_bf16 v[58:61], v[110:113], v[98:101], v[58:61]
	ds_write_b128 v24, v[142:145] offset:61440
	s_waitcnt vmcnt(6)
	ds_write_b128 v25, v[178:181] offset:61440
	v_mfma_f32_16x16x32_bf16 v[62:65], v[114:117], v[98:101], v[62:65]
	v_mfma_f32_16x16x32_bf16 v[74:77], v[118:121], v[98:101], v[74:77]
	v_mfma_f32_16x16x32_bf16 v[46:49], v[122:125], v[98:101], v[46:49]
	v_mfma_f32_16x16x32_bf16 v[66:69], v[110:113], v[102:105], v[66:69]
	ds_write_b128 v26, v[152:155] offset:61440
	v_mfma_f32_16x16x32_bf16 v[78:81], v[114:117], v[102:105], v[78:81]
	v_mfma_f32_16x16x32_bf16 v[82:85], v[118:121], v[102:105], v[82:85]
	v_mfma_f32_16x16x32_bf16 v[50:53], v[122:125], v[102:105], v[50:53]
	v_mfma_f32_16x16x32_bf16 v[70:73], v[110:113], v[106:109], v[70:73]
	ds_write_b128 v27, v[156:159] offset:61440
	v_mfma_f32_16x16x32_bf16 v[86:89], v[114:117], v[106:109], v[86:89]
	v_mfma_f32_16x16x32_bf16 v[90:93], v[118:121], v[106:109], v[90:93]
	v_mfma_f32_16x16x32_bf16 v[54:57], v[122:125], v[106:109], v[54:57]
	s_waitcnt lgkmcnt(0)
	s_barrier
	ds_read_b128 v[94:97], v39 offset:61440
	ds_read_b128 v[98:101], v39 offset:64000
	ds_read_b128 v[102:105], v32 offset:5120
	ds_read_b128 v[106:109], v32 offset:7680
	ds_read_b128 v[110:113], v33
	ds_read_b128 v[114:117], v33 offset:2560
	ds_read_b128 v[118:121], v33 offset:5120
	ds_read_b128 v[122:125], v33 offset:7680
	v_mfma_f32_16x16x32_bf16 v[126:129], v[222:225], v[206:209], v[126:129]
	v_mfma_f32_16x16x32_bf16 v[130:133], v[226:229], v[206:209], v[130:133]
	v_mfma_f32_16x16x32_bf16 v[134:137], v[230:233], v[206:209], v[134:137]
	v_mfma_f32_16x16x32_bf16 v[42:45], v[234:237], v[206:209], v[42:45]
	v_mfma_f32_16x16x32_bf16 v[58:61], v[222:225], v[210:213], v[58:61]
	v_mfma_f32_16x16x32_bf16 v[62:65], v[226:229], v[210:213], v[62:65]
	v_mfma_f32_16x16x32_bf16 v[74:77], v[230:233], v[210:213], v[74:77]
	v_mfma_f32_16x16x32_bf16 v[46:49], v[234:237], v[210:213], v[46:49]
	v_mfma_f32_16x16x32_bf16 v[66:69], v[222:225], v[214:217], v[66:69]
	v_mfma_f32_16x16x32_bf16 v[78:81], v[226:229], v[214:217], v[78:81]
	v_mfma_f32_16x16x32_bf16 v[82:85], v[230:233], v[214:217], v[82:85]
	v_mfma_f32_16x16x32_bf16 v[50:53], v[234:237], v[214:217], v[50:53]
	v_mfma_f32_16x16x32_bf16 v[70:73], v[222:225], v[218:221], v[70:73]
	v_mfma_f32_16x16x32_bf16 v[86:89], v[226:229], v[218:221], v[86:89]
	v_mfma_f32_16x16x32_bf16 v[90:93], v[230:233], v[218:221], v[90:93]
	v_mfma_f32_16x16x32_bf16 v[54:57], v[234:237], v[218:221], v[54:57]
	global_load_dwordx4 v[138:141], v[2:3], off offset:1152
	global_load_dwordx4 v[142:145], v[8:9], off offset:1152
	global_load_dwordx4 v[152:155], v[10:11], off offset:1152
	global_load_dwordx4 v[156:159], v[12:13], off offset:1152
	global_load_dwordx4 v[174:177], v[14:15], off offset:1152
	global_load_dwordx4 v[178:181], v[16:17], off offset:1152
	ds_read_b128 v[206:209], v30 offset:61504
	ds_read_b128 v[210:213], v30 offset:64064
	ds_read_b128 v[214:217], v34 offset:64
	ds_read_b128 v[218:221], v35 offset:64
	ds_read_b128 v[222:225], v41 offset:64
	ds_read_b128 v[226:229], v36 offset:64
	ds_read_b128 v[230:233], v37 offset:64
	ds_read_b128 v[234:237], v38 offset:64
	s_waitcnt lgkmcnt(11)
;     ...
;   for (int k0 = 0; k0 < K; k0 += 128) {
;     G_READ(fa1, fb1, 0, 32);
;     if (k0 + 128 < K) G_LOAD(ra0, rb0, k0 + 128);
;     __builtin_amdgcn_sched_barrier(0);
;     G_MFMA_ST(fa0, fb0, ra1, rb1, 1);
;     __syncthreads();
;     G_READ(fa0, fb0, 1, 0);
;     __builtin_amdgcn_sched_barrier(0);
;     G_MFMA(fa1, fb1);
;     __builtin_amdgcn_sched_barrier(0);
;     G_READ(fa1, fb1, 1, 32);
;     if (k0 + 192 < K) G_LOAD(ra1, rb1, k0 + 192);
;     __builtin_amdgcn_sched_barrier(0);
;     if (k0 + 128 < K) {
;       G_MFMA_ST(fa0, fb0, ra0, rb0, 0);
;       __syncthreads();
;       G_READ(fa0, fb0, 0, 0);
;     } else {
;       G_MFMA(fa0, fb0);
;     }
;     __builtin_amdgcn_sched_barrier(0);
;     G_MFMA(fa1, fb1);
;     __builtin_amdgcn_sched_barrier(0);
;   }
	v_mfma_f32_16x16x32_bf16 v[126:129], v[110:113], v[94:97], v[126:129]
	s_waitcnt vmcnt(11)
	ds_write_b128 v22, v[182:185]
	s_waitcnt vmcnt(7)
	ds_write_b128 v23, v[198:201]
	s_waitcnt lgkmcnt(12)
	v_mfma_f32_16x16x32_bf16 v[130:133], v[114:117], v[94:97], v[130:133]
	s_waitcnt lgkmcnt(11)
	v_mfma_f32_16x16x32_bf16 v[134:137], v[118:121], v[94:97], v[134:137]
	s_waitcnt lgkmcnt(10)
	v_mfma_f32_16x16x32_bf16 v[42:45], v[122:125], v[94:97], v[42:45]
	v_mfma_f32_16x16x32_bf16 v[58:61], v[110:113], v[98:101], v[58:61]
	ds_write_b128 v22, v[186:189] offset:10240
	s_waitcnt vmcnt(6)
	ds_write_b128 v25, v[202:205]
	v_mfma_f32_16x16x32_bf16 v[62:65], v[114:117], v[98:101], v[62:65]
	v_mfma_f32_16x16x32_bf16 v[74:77], v[118:121], v[98:101], v[74:77]
	v_mfma_f32_16x16x32_bf16 v[46:49], v[122:125], v[98:101], v[46:49]
	v_mfma_f32_16x16x32_bf16 v[66:69], v[110:113], v[102:105], v[66:69]
	ds_write_b128 v22, v[190:193] offset:20480
	v_mfma_f32_16x16x32_bf16 v[78:81], v[114:117], v[102:105], v[78:81]
	v_mfma_f32_16x16x32_bf16 v[82:85], v[118:121], v[102:105], v[82:85]
	v_mfma_f32_16x16x32_bf16 v[50:53], v[122:125], v[102:105], v[50:53]
	v_mfma_f32_16x16x32_bf16 v[70:73], v[110:113], v[106:109], v[70:73]
	ds_write_b128 v22, v[194:197] offset:30720
	v_mfma_f32_16x16x32_bf16 v[86:89], v[114:117], v[106:109], v[86:89]
	v_mfma_f32_16x16x32_bf16 v[90:93], v[118:121], v[106:109], v[90:93]
	v_mfma_f32_16x16x32_bf16 v[54:57], v[122:125], v[106:109], v[54:57]
	s_waitcnt lgkmcnt(0)
	s_barrier
	ds_read_b128 v[94:97], v39
	ds_read_b128 v[98:101], v39 offset:2560
	ds_read_b128 v[102:105], v39 offset:5120
	ds_read_b128 v[106:109], v39 offset:7680
	ds_read_b128 v[110:113], v40 offset:40960
	ds_read_b128 v[114:117], v40 offset:43520
	ds_read_b128 v[118:121], v40 offset:46080
	ds_read_b128 v[122:125], v40 offset:48640
	v_mfma_f32_16x16x32_bf16 v[126:129], v[222:225], v[206:209], v[126:129]
	v_mfma_f32_16x16x32_bf16 v[130:133], v[226:229], v[206:209], v[130:133]
	v_mfma_f32_16x16x32_bf16 v[134:137], v[230:233], v[206:209], v[134:137]
	v_mfma_f32_16x16x32_bf16 v[42:45], v[234:237], v[206:209], v[42:45]
	v_mfma_f32_16x16x32_bf16 v[58:61], v[222:225], v[210:213], v[58:61]
	v_mfma_f32_16x16x32_bf16 v[62:65], v[226:229], v[210:213], v[62:65]
	v_mfma_f32_16x16x32_bf16 v[74:77], v[230:233], v[210:213], v[74:77]
	v_mfma_f32_16x16x32_bf16 v[46:49], v[234:237], v[210:213], v[46:49]
	v_mfma_f32_16x16x32_bf16 v[66:69], v[222:225], v[214:217], v[66:69]
	v_mfma_f32_16x16x32_bf16 v[78:81], v[226:229], v[214:217], v[78:81]
	v_mfma_f32_16x16x32_bf16 v[82:85], v[230:233], v[214:217], v[82:85]
	v_mfma_f32_16x16x32_bf16 v[50:53], v[234:237], v[214:217], v[50:53]
	v_mfma_f32_16x16x32_bf16 v[70:73], v[222:225], v[218:221], v[70:73]
	v_mfma_f32_16x16x32_bf16 v[86:89], v[226:229], v[218:221], v[86:89]
	v_mfma_f32_16x16x32_bf16 v[90:93], v[230:233], v[218:221], v[90:93]
	v_mfma_f32_16x16x32_bf16 v[54:57], v[234:237], v[218:221], v[54:57]
	global_load_dwordx4 v[182:185], v[2:3], off offset:1280
	global_load_dwordx4 v[186:189], v[8:9], off offset:1280
	global_load_dwordx4 v[190:193], v[10:11], off offset:1280
	global_load_dwordx4 v[194:197], v[12:13], off offset:1280
	global_load_dwordx4 v[198:201], v[14:15], off offset:1280
	global_load_dwordx4 v[202:205], v[16:17], off offset:1280
	ds_read_b128 v[206:209], v30 offset:64
	ds_read_b128 v[210:213], v30 offset:2624
	ds_read_b128 v[214:217], v30 offset:5184
	ds_read_b128 v[218:221], v30 offset:7744
	ds_read_b128 v[222:225], v31 offset:41024
	ds_read_b128 v[226:229], v31 offset:43584
	ds_read_b128 v[230:233], v31 offset:46144
	ds_read_b128 v[234:237], v31 offset:48704
	s_waitcnt lgkmcnt(11)
	v_mfma_f32_16x16x32_bf16 v[126:129], v[110:113], v[94:97], v[126:129]
	s_waitcnt vmcnt(11)
	ds_write_b128 v22, v[138:141] offset:61440
	s_waitcnt vmcnt(7)
	ds_write_b128 v23, v[174:177] offset:61440
	s_waitcnt lgkmcnt(12)
	v_mfma_f32_16x16x32_bf16 v[130:133], v[114:117], v[94:97], v[130:133]
	s_waitcnt lgkmcnt(11)
	v_mfma_f32_16x16x32_bf16 v[134:137], v[118:121], v[94:97], v[134:137]
	s_waitcnt lgkmcnt(10)
	v_mfma_f32_16x16x32_bf16 v[42:45], v[122:125], v[94:97], v[42:45]
	v_mfma_f32_16x16x32_bf16 v[58:61], v[110:113], v[98:101], v[58:61]
	ds_write_b128 v24, v[142:145] offset:61440
	s_waitcnt vmcnt(6)
	ds_write_b128 v25, v[178:181] offset:61440
	v_mfma_f32_16x16x32_bf16 v[62:65], v[114:117], v[98:101], v[62:65]
	v_mfma_f32_16x16x32_bf16 v[74:77], v[118:121], v[98:101], v[74:77]
	v_mfma_f32_16x16x32_bf16 v[46:49], v[122:125], v[98:101], v[46:49]
	v_mfma_f32_16x16x32_bf16 v[66:69], v[110:113], v[102:105], v[66:69]
	ds_write_b128 v26, v[152:155] offset:61440
	v_mfma_f32_16x16x32_bf16 v[78:81], v[114:117], v[102:105], v[78:81]
	v_mfma_f32_16x16x32_bf16 v[82:85], v[118:121], v[102:105], v[82:85]
	v_mfma_f32_16x16x32_bf16 v[50:53], v[122:125], v[102:105], v[50:53]
	v_mfma_f32_16x16x32_bf16 v[70:73], v[110:113], v[106:109], v[70:73]
	ds_write_b128 v27, v[156:159] offset:61440
	v_mfma_f32_16x16x32_bf16 v[86:89], v[114:117], v[106:109], v[86:89]
	v_mfma_f32_16x16x32_bf16 v[90:93], v[118:121], v[106:109], v[90:93]
	v_mfma_f32_16x16x32_bf16 v[54:57], v[122:125], v[106:109], v[54:57]
	s_waitcnt lgkmcnt(0)
	s_barrier
;     ...
;   for (int k0 = 0; k0 < K; k0 += 128) {
;     G_READ(fa1, fb1, 0, 32);
;     if (k0 + 128 < K) G_LOAD(ra0, rb0, k0 + 128);
;     __builtin_amdgcn_sched_barrier(0);
;     G_MFMA_ST(fa0, fb0, ra1, rb1, 1);
;     __syncthreads();
;     G_READ(fa0, fb0, 1, 0);
;     __builtin_amdgcn_sched_barrier(0);
;     G_MFMA(fa1, fb1);
;     __builtin_amdgcn_sched_barrier(0);
;     G_READ(fa1, fb1, 1, 32);
;     if (k0 + 192 < K) G_LOAD(ra1, rb1, k0 + 192);
;     __builtin_amdgcn_sched_barrier(0);
;     if (k0 + 128 < K) {
;       G_MFMA_ST(fa0, fb0, ra0, rb0, 0);
;       __syncthreads();
;       G_READ(fa0, fb0, 0, 0);
;     } else {
;       G_MFMA(fa0, fb0);
;     }
;     __builtin_amdgcn_sched_barrier(0);
;     G_MFMA(fa1, fb1);
;     __builtin_amdgcn_sched_barrier(0);
;   }
	ds_read_b128 v[94:97], v39 offset:61440
	ds_read_b128 v[98:101], v39 offset:64000
	ds_read_b128 v[102:105], v32 offset:5120
	ds_read_b128 v[106:109], v32 offset:7680
	ds_read_b128 v[110:113], v33
	ds_read_b128 v[114:117], v33 offset:2560
	ds_read_b128 v[118:121], v33 offset:5120
	ds_read_b128 v[122:125], v33 offset:7680
	v_mfma_f32_16x16x32_bf16 v[126:129], v[222:225], v[206:209], v[126:129]
	v_mfma_f32_16x16x32_bf16 v[130:133], v[226:229], v[206:209], v[130:133]
	v_mfma_f32_16x16x32_bf16 v[134:137], v[230:233], v[206:209], v[134:137]
	v_mfma_f32_16x16x32_bf16 v[42:45], v[234:237], v[206:209], v[42:45]
	v_mfma_f32_16x16x32_bf16 v[58:61], v[222:225], v[210:213], v[58:61]
	v_mfma_f32_16x16x32_bf16 v[62:65], v[226:229], v[210:213], v[62:65]
	v_mfma_f32_16x16x32_bf16 v[74:77], v[230:233], v[210:213], v[74:77]
	v_mfma_f32_16x16x32_bf16 v[46:49], v[234:237], v[210:213], v[46:49]
	v_mfma_f32_16x16x32_bf16 v[66:69], v[222:225], v[214:217], v[66:69]
	v_mfma_f32_16x16x32_bf16 v[78:81], v[226:229], v[214:217], v[78:81]
	v_mfma_f32_16x16x32_bf16 v[82:85], v[230:233], v[214:217], v[82:85]
	v_mfma_f32_16x16x32_bf16 v[50:53], v[234:237], v[214:217], v[50:53]
	v_mfma_f32_16x16x32_bf16 v[70:73], v[222:225], v[218:221], v[70:73]
	v_mfma_f32_16x16x32_bf16 v[86:89], v[226:229], v[218:221], v[86:89]
	v_mfma_f32_16x16x32_bf16 v[90:93], v[230:233], v[218:221], v[90:93]
	v_mfma_f32_16x16x32_bf16 v[54:57], v[234:237], v[218:221], v[54:57]
	global_load_dwordx4 v[138:141], v[2:3], off offset:1408
	global_load_dwordx4 v[142:145], v[8:9], off offset:1408
	global_load_dwordx4 v[152:155], v[10:11], off offset:1408
	global_load_dwordx4 v[156:159], v[12:13], off offset:1408
	global_load_dwordx4 v[174:177], v[14:15], off offset:1408
	global_load_dwordx4 v[178:181], v[16:17], off offset:1408
	ds_read_b128 v[206:209], v30 offset:61504
	ds_read_b128 v[210:213], v30 offset:64064
	ds_read_b128 v[214:217], v34 offset:64
	ds_read_b128 v[218:221], v35 offset:64
	ds_read_b128 v[222:225], v41 offset:64
	ds_read_b128 v[226:229], v36 offset:64
	ds_read_b128 v[230:233], v37 offset:64
	ds_read_b128 v[234:237], v38 offset:64
	s_waitcnt lgkmcnt(11)
	v_mfma_f32_16x16x32_bf16 v[126:129], v[110:113], v[94:97], v[126:129]
	s_waitcnt vmcnt(11)
	ds_write_b128 v22, v[182:185]
	s_waitcnt vmcnt(7)
	ds_write_b128 v23, v[198:201]
	s_waitcnt lgkmcnt(12)
	v_mfma_f32_16x16x32_bf16 v[130:133], v[114:117], v[94:97], v[130:133]
	s_waitcnt lgkmcnt(11)
	v_mfma_f32_16x16x32_bf16 v[134:137], v[118:121], v[94:97], v[134:137]
	s_waitcnt lgkmcnt(10)
	v_mfma_f32_16x16x32_bf16 v[42:45], v[122:125], v[94:97], v[42:45]
	v_mfma_f32_16x16x32_bf16 v[58:61], v[110:113], v[98:101], v[58:61]
	ds_write_b128 v22, v[186:189] offset:10240
	s_waitcnt vmcnt(6)
	ds_write_b128 v25, v[202:205]
	v_mfma_f32_16x16x32_bf16 v[62:65], v[114:117], v[98:101], v[62:65]
	v_mfma_f32_16x16x32_bf16 v[74:77], v[118:121], v[98:101], v[74:77]
	v_mfma_f32_16x16x32_bf16 v[46:49], v[122:125], v[98:101], v[46:49]
	v_mfma_f32_16x16x32_bf16 v[66:69], v[110:113], v[102:105], v[66:69]
	ds_write_b128 v22, v[190:193] offset:20480
	v_mfma_f32_16x16x32_bf16 v[78:81], v[114:117], v[102:105], v[78:81]
	v_mfma_f32_16x16x32_bf16 v[82:85], v[118:121], v[102:105], v[82:85]
	v_mfma_f32_16x16x32_bf16 v[50:53], v[122:125], v[102:105], v[50:53]
	v_mfma_f32_16x16x32_bf16 v[70:73], v[110:113], v[106:109], v[70:73]
	ds_write_b128 v22, v[194:197] offset:30720
	v_mfma_f32_16x16x32_bf16 v[86:89], v[114:117], v[106:109], v[86:89]
	v_mfma_f32_16x16x32_bf16 v[90:93], v[118:121], v[106:109], v[90:93]
	v_mfma_f32_16x16x32_bf16 v[54:57], v[122:125], v[106:109], v[54:57]
	s_waitcnt lgkmcnt(0)
	s_barrier
	ds_read_b128 v[94:97], v39
	ds_read_b128 v[98:101], v39 offset:2560
	ds_read_b128 v[102:105], v39 offset:5120
	ds_read_b128 v[106:109], v39 offset:7680
	ds_read_b128 v[110:113], v40 offset:40960
	ds_read_b128 v[114:117], v40 offset:43520
	ds_read_b128 v[118:121], v40 offset:46080
	ds_read_b128 v[122:125], v40 offset:48640
	v_mfma_f32_16x16x32_bf16 v[126:129], v[222:225], v[206:209], v[126:129]
	v_mfma_f32_16x16x32_bf16 v[130:133], v[226:229], v[206:209], v[130:133]
	v_mfma_f32_16x16x32_bf16 v[134:137], v[230:233], v[206:209], v[134:137]
	v_mfma_f32_16x16x32_bf16 v[42:45], v[234:237], v[206:209], v[42:45]
	v_mfma_f32_16x16x32_bf16 v[58:61], v[222:225], v[210:213], v[58:61]
	v_mfma_f32_16x16x32_bf16 v[62:65], v[226:229], v[210:213], v[62:65]
	v_mfma_f32_16x16x32_bf16 v[74:77], v[230:233], v[210:213], v[74:77]
	v_mfma_f32_16x16x32_bf16 v[46:49], v[234:237], v[210:213], v[46:49]
	v_mfma_f32_16x16x32_bf16 v[66:69], v[222:225], v[214:217], v[66:69]
	v_mfma_f32_16x16x32_bf16 v[78:81], v[226:229], v[214:217], v[78:81]
	v_mfma_f32_16x16x32_bf16 v[82:85], v[230:233], v[214:217], v[82:85]
	v_mfma_f32_16x16x32_bf16 v[50:53], v[234:237], v[214:217], v[50:53]
	v_mfma_f32_16x16x32_bf16 v[70:73], v[222:225], v[218:221], v[70:73]
	v_mfma_f32_16x16x32_bf16 v[86:89], v[226:229], v[218:221], v[86:89]
	v_mfma_f32_16x16x32_bf16 v[90:93], v[230:233], v[218:221], v[90:93]
	v_mfma_f32_16x16x32_bf16 v[54:57], v[234:237], v[218:221], v[54:57]
	global_load_dwordx4 v[182:185], v[2:3], off offset:1536
	global_load_dwordx4 v[186:189], v[8:9], off offset:1536
	global_load_dwordx4 v[190:193], v[10:11], off offset:1536
	global_load_dwordx4 v[194:197], v[12:13], off offset:1536
	global_load_dwordx4 v[198:201], v[14:15], off offset:1536
	global_load_dwordx4 v[202:205], v[16:17], off offset:1536
	ds_read_b128 v[206:209], v30 offset:64
	ds_read_b128 v[210:213], v30 offset:2624
	ds_read_b128 v[214:217], v30 offset:5184
	ds_read_b128 v[218:221], v30 offset:7744
	ds_read_b128 v[222:225], v31 offset:41024
	ds_read_b128 v[226:229], v31 offset:43584
	ds_read_b128 v[230:233], v31 offset:46144
	ds_read_b128 v[234:237], v31 offset:48704
	s_waitcnt lgkmcnt(11)
;     ...
;   for (int k0 = 0; k0 < K; k0 += 128) {
;     G_READ(fa1, fb1, 0, 32);
;     if (k0 + 128 < K) G_LOAD(ra0, rb0, k0 + 128);
;     __builtin_amdgcn_sched_barrier(0);
;     G_MFMA_ST(fa0, fb0, ra1, rb1, 1);
;     __syncthreads();
;     G_READ(fa0, fb0, 1, 0);
;     __builtin_amdgcn_sched_barrier(0);
;     G_MFMA(fa1, fb1);
;     __builtin_amdgcn_sched_barrier(0);
;     G_READ(fa1, fb1, 1, 32);
;     if (k0 + 192 < K) G_LOAD(ra1, rb1, k0 + 192);
;     __builtin_amdgcn_sched_barrier(0);
;     if (k0 + 128 < K) {
;       G_MFMA_ST(fa0, fb0, ra0, rb0, 0);
;       __syncthreads();
;       G_READ(fa0, fb0, 0, 0);
;     } else {
;       G_MFMA(fa0, fb0);
;     }
;     __builtin_amdgcn_sched_barrier(0);
;     G_MFMA(fa1, fb1);
;     __builtin_amdgcn_sched_barrier(0);
;   }
	v_mfma_f32_16x16x32_bf16 v[126:129], v[110:113], v[94:97], v[126:129]
	s_waitcnt vmcnt(11)
	ds_write_b128 v22, v[138:141] offset:61440
	s_waitcnt vmcnt(7)
	ds_write_b128 v23, v[174:177] offset:61440
	s_waitcnt lgkmcnt(12)
	v_mfma_f32_16x16x32_bf16 v[130:133], v[114:117], v[94:97], v[130:133]
	s_waitcnt lgkmcnt(11)
	v_mfma_f32_16x16x32_bf16 v[134:137], v[118:121], v[94:97], v[134:137]
	s_waitcnt lgkmcnt(10)
	v_mfma_f32_16x16x32_bf16 v[42:45], v[122:125], v[94:97], v[42:45]
	v_mfma_f32_16x16x32_bf16 v[58:61], v[110:113], v[98:101], v[58:61]
	ds_write_b128 v24, v[142:145] offset:61440
	s_waitcnt vmcnt(6)
	ds_write_b128 v25, v[178:181] offset:61440
	v_mfma_f32_16x16x32_bf16 v[62:65], v[114:117], v[98:101], v[62:65]
	v_mfma_f32_16x16x32_bf16 v[74:77], v[118:121], v[98:101], v[74:77]
	v_mfma_f32_16x16x32_bf16 v[46:49], v[122:125], v[98:101], v[46:49]
	v_mfma_f32_16x16x32_bf16 v[66:69], v[110:113], v[102:105], v[66:69]
	ds_write_b128 v26, v[152:155] offset:61440
	v_mfma_f32_16x16x32_bf16 v[78:81], v[114:117], v[102:105], v[78:81]
	v_mfma_f32_16x16x32_bf16 v[82:85], v[118:121], v[102:105], v[82:85]
	v_mfma_f32_16x16x32_bf16 v[50:53], v[122:125], v[102:105], v[50:53]
	v_mfma_f32_16x16x32_bf16 v[70:73], v[110:113], v[106:109], v[70:73]
	ds_write_b128 v27, v[156:159] offset:61440
	v_mfma_f32_16x16x32_bf16 v[86:89], v[114:117], v[106:109], v[86:89]
	v_mfma_f32_16x16x32_bf16 v[90:93], v[118:121], v[106:109], v[90:93]
	v_mfma_f32_16x16x32_bf16 v[54:57], v[122:125], v[106:109], v[54:57]
	s_waitcnt lgkmcnt(0)
	s_barrier
	ds_read_b128 v[94:97], v39 offset:61440
	ds_read_b128 v[98:101], v39 offset:64000
	ds_read_b128 v[102:105], v32 offset:5120
	ds_read_b128 v[106:109], v32 offset:7680
	ds_read_b128 v[110:113], v33
	ds_read_b128 v[114:117], v33 offset:2560
	ds_read_b128 v[118:121], v33 offset:5120
	ds_read_b128 v[122:125], v33 offset:7680
	v_mfma_f32_16x16x32_bf16 v[126:129], v[222:225], v[206:209], v[126:129]
	v_mfma_f32_16x16x32_bf16 v[130:133], v[226:229], v[206:209], v[130:133]
	v_mfma_f32_16x16x32_bf16 v[134:137], v[230:233], v[206:209], v[134:137]
	v_mfma_f32_16x16x32_bf16 v[42:45], v[234:237], v[206:209], v[42:45]
	v_mfma_f32_16x16x32_bf16 v[58:61], v[222:225], v[210:213], v[58:61]
	v_mfma_f32_16x16x32_bf16 v[62:65], v[226:229], v[210:213], v[62:65]
	v_mfma_f32_16x16x32_bf16 v[74:77], v[230:233], v[210:213], v[74:77]
	v_mfma_f32_16x16x32_bf16 v[46:49], v[234:237], v[210:213], v[46:49]
	v_mfma_f32_16x16x32_bf16 v[66:69], v[222:225], v[214:217], v[66:69]
	v_mfma_f32_16x16x32_bf16 v[78:81], v[226:229], v[214:217], v[78:81]
	v_mfma_f32_16x16x32_bf16 v[82:85], v[230:233], v[214:217], v[82:85]
	v_mfma_f32_16x16x32_bf16 v[50:53], v[234:237], v[214:217], v[50:53]
	v_mfma_f32_16x16x32_bf16 v[70:73], v[222:225], v[218:221], v[70:73]
	v_mfma_f32_16x16x32_bf16 v[86:89], v[226:229], v[218:221], v[86:89]
	v_mfma_f32_16x16x32_bf16 v[90:93], v[230:233], v[218:221], v[90:93]
	v_mfma_f32_16x16x32_bf16 v[54:57], v[234:237], v[218:221], v[54:57]
	global_load_dwordx4 v[138:141], v[2:3], off offset:1664
	global_load_dwordx4 v[142:145], v[8:9], off offset:1664
	global_load_dwordx4 v[152:155], v[10:11], off offset:1664
	global_load_dwordx4 v[156:159], v[12:13], off offset:1664
	global_load_dwordx4 v[174:177], v[14:15], off offset:1664
	global_load_dwordx4 v[178:181], v[16:17], off offset:1664
	ds_read_b128 v[206:209], v30 offset:61504
	ds_read_b128 v[210:213], v30 offset:64064
	ds_read_b128 v[214:217], v34 offset:64
	ds_read_b128 v[218:221], v35 offset:64
	ds_read_b128 v[222:225], v41 offset:64
	ds_read_b128 v[226:229], v36 offset:64
	ds_read_b128 v[230:233], v37 offset:64
	ds_read_b128 v[234:237], v38 offset:64
	s_waitcnt lgkmcnt(11)
	v_mfma_f32_16x16x32_bf16 v[126:129], v[110:113], v[94:97], v[126:129]
	s_waitcnt vmcnt(11)
	ds_write_b128 v22, v[182:185]
	s_waitcnt vmcnt(7)
	ds_write_b128 v23, v[198:201]
	s_waitcnt lgkmcnt(12)
	v_mfma_f32_16x16x32_bf16 v[130:133], v[114:117], v[94:97], v[130:133]
	s_waitcnt lgkmcnt(11)
	v_mfma_f32_16x16x32_bf16 v[134:137], v[118:121], v[94:97], v[134:137]
	s_waitcnt lgkmcnt(10)
	v_mfma_f32_16x16x32_bf16 v[42:45], v[122:125], v[94:97], v[42:45]
	v_mfma_f32_16x16x32_bf16 v[58:61], v[110:113], v[98:101], v[58:61]
	ds_write_b128 v22, v[186:189] offset:10240
	s_waitcnt vmcnt(6)
	ds_write_b128 v25, v[202:205]
	v_mfma_f32_16x16x32_bf16 v[62:65], v[114:117], v[98:101], v[62:65]
	v_mfma_f32_16x16x32_bf16 v[74:77], v[118:121], v[98:101], v[74:77]
	v_mfma_f32_16x16x32_bf16 v[46:49], v[122:125], v[98:101], v[46:49]
	v_mfma_f32_16x16x32_bf16 v[66:69], v[110:113], v[102:105], v[66:69]
	ds_write_b128 v22, v[190:193] offset:20480
	v_mfma_f32_16x16x32_bf16 v[78:81], v[114:117], v[102:105], v[78:81]
	v_mfma_f32_16x16x32_bf16 v[82:85], v[118:121], v[102:105], v[82:85]
	v_mfma_f32_16x16x32_bf16 v[50:53], v[122:125], v[102:105], v[50:53]
	v_mfma_f32_16x16x32_bf16 v[70:73], v[110:113], v[106:109], v[70:73]
	ds_write_b128 v22, v[194:197] offset:30720
	v_mfma_f32_16x16x32_bf16 v[86:89], v[114:117], v[106:109], v[86:89]
	v_mfma_f32_16x16x32_bf16 v[90:93], v[118:121], v[106:109], v[90:93]
	v_mfma_f32_16x16x32_bf16 v[54:57], v[122:125], v[106:109], v[54:57]
	s_waitcnt lgkmcnt(0)
	s_barrier
;     ...
;   for (int k0 = 0; k0 < K; k0 += 128) {
;     G_READ(fa1, fb1, 0, 32);
;     if (k0 + 128 < K) G_LOAD(ra0, rb0, k0 + 128);
;     __builtin_amdgcn_sched_barrier(0);
;     G_MFMA_ST(fa0, fb0, ra1, rb1, 1);
;     __syncthreads();
;     G_READ(fa0, fb0, 1, 0);
;     __builtin_amdgcn_sched_barrier(0);
;     G_MFMA(fa1, fb1);
;     __builtin_amdgcn_sched_barrier(0);
;     G_READ(fa1, fb1, 1, 32);
;     if (k0 + 192 < K) G_LOAD(ra1, rb1, k0 + 192);
;     __builtin_amdgcn_sched_barrier(0);
;     if (k0 + 128 < K) {
;       G_MFMA_ST(fa0, fb0, ra0, rb0, 0);
;       __syncthreads();
;       G_READ(fa0, fb0, 0, 0);
;     } else {
;       G_MFMA(fa0, fb0);
;     }
;     __builtin_amdgcn_sched_barrier(0);
;     G_MFMA(fa1, fb1);
;     __builtin_amdgcn_sched_barrier(0);
;   }
	ds_read_b128 v[94:97], v39
	ds_read_b128 v[98:101], v39 offset:2560
	ds_read_b128 v[102:105], v39 offset:5120
	ds_read_b128 v[106:109], v39 offset:7680
	ds_read_b128 v[110:113], v40 offset:40960
	ds_read_b128 v[114:117], v40 offset:43520
	ds_read_b128 v[118:121], v40 offset:46080
	ds_read_b128 v[122:125], v40 offset:48640
	v_mfma_f32_16x16x32_bf16 v[126:129], v[222:225], v[206:209], v[126:129]
	v_mfma_f32_16x16x32_bf16 v[130:133], v[226:229], v[206:209], v[130:133]
	v_mfma_f32_16x16x32_bf16 v[134:137], v[230:233], v[206:209], v[134:137]
	v_mfma_f32_16x16x32_bf16 v[42:45], v[234:237], v[206:209], v[42:45]
	v_mfma_f32_16x16x32_bf16 v[58:61], v[222:225], v[210:213], v[58:61]
	v_mfma_f32_16x16x32_bf16 v[62:65], v[226:229], v[210:213], v[62:65]
	v_mfma_f32_16x16x32_bf16 v[74:77], v[230:233], v[210:213], v[74:77]
	v_mfma_f32_16x16x32_bf16 v[46:49], v[234:237], v[210:213], v[46:49]
	v_mfma_f32_16x16x32_bf16 v[66:69], v[222:225], v[214:217], v[66:69]
	v_mfma_f32_16x16x32_bf16 v[78:81], v[226:229], v[214:217], v[78:81]
	v_mfma_f32_16x16x32_bf16 v[82:85], v[230:233], v[214:217], v[82:85]
	v_mfma_f32_16x16x32_bf16 v[50:53], v[234:237], v[214:217], v[50:53]
	v_mfma_f32_16x16x32_bf16 v[70:73], v[222:225], v[218:221], v[70:73]
	v_mfma_f32_16x16x32_bf16 v[86:89], v[226:229], v[218:221], v[86:89]
	v_mfma_f32_16x16x32_bf16 v[90:93], v[230:233], v[218:221], v[90:93]
	v_mfma_f32_16x16x32_bf16 v[54:57], v[234:237], v[218:221], v[54:57]
	global_load_dwordx4 v[182:185], v[2:3], off offset:1792
	global_load_dwordx4 v[186:189], v[8:9], off offset:1792
	global_load_dwordx4 v[190:193], v[10:11], off offset:1792
	global_load_dwordx4 v[194:197], v[12:13], off offset:1792
	global_load_dwordx4 v[198:201], v[14:15], off offset:1792
	global_load_dwordx4 v[202:205], v[16:17], off offset:1792
	ds_read_b128 v[206:209], v30 offset:64
	ds_read_b128 v[210:213], v30 offset:2624
	ds_read_b128 v[214:217], v30 offset:5184
	ds_read_b128 v[218:221], v30 offset:7744
	ds_read_b128 v[222:225], v31 offset:41024
	ds_read_b128 v[226:229], v31 offset:43584
	ds_read_b128 v[230:233], v31 offset:46144
	ds_read_b128 v[234:237], v31 offset:48704
	s_waitcnt lgkmcnt(11)
	v_mfma_f32_16x16x32_bf16 v[126:129], v[110:113], v[94:97], v[126:129]
	s_waitcnt vmcnt(11)
	ds_write_b128 v22, v[138:141] offset:61440
	s_waitcnt vmcnt(7)
	ds_write_b128 v23, v[174:177] offset:61440
	s_waitcnt lgkmcnt(12)
	v_mfma_f32_16x16x32_bf16 v[130:133], v[114:117], v[94:97], v[130:133]
	s_waitcnt lgkmcnt(11)
	v_mfma_f32_16x16x32_bf16 v[134:137], v[118:121], v[94:97], v[134:137]
	s_waitcnt lgkmcnt(10)
	v_mfma_f32_16x16x32_bf16 v[42:45], v[122:125], v[94:97], v[42:45]
	v_mfma_f32_16x16x32_bf16 v[58:61], v[110:113], v[98:101], v[58:61]
	ds_write_b128 v24, v[142:145] offset:61440
	s_waitcnt vmcnt(6)
	ds_write_b128 v25, v[178:181] offset:61440
	v_mfma_f32_16x16x32_bf16 v[62:65], v[114:117], v[98:101], v[62:65]
	v_mfma_f32_16x16x32_bf16 v[74:77], v[118:121], v[98:101], v[74:77]
	v_mfma_f32_16x16x32_bf16 v[46:49], v[122:125], v[98:101], v[46:49]
	v_mfma_f32_16x16x32_bf16 v[66:69], v[110:113], v[102:105], v[66:69]
	ds_write_b128 v26, v[152:155] offset:61440
	v_mfma_f32_16x16x32_bf16 v[78:81], v[114:117], v[102:105], v[78:81]
	v_mfma_f32_16x16x32_bf16 v[82:85], v[118:121], v[102:105], v[82:85]
	v_mfma_f32_16x16x32_bf16 v[50:53], v[122:125], v[102:105], v[50:53]
	v_mfma_f32_16x16x32_bf16 v[70:73], v[110:113], v[106:109], v[70:73]
	ds_write_b128 v27, v[156:159] offset:61440
	v_mfma_f32_16x16x32_bf16 v[86:89], v[114:117], v[106:109], v[86:89]
	v_mfma_f32_16x16x32_bf16 v[90:93], v[118:121], v[106:109], v[90:93]
	v_mfma_f32_16x16x32_bf16 v[54:57], v[122:125], v[106:109], v[54:57]
	s_waitcnt lgkmcnt(0)
	s_barrier
	ds_read_b128 v[94:97], v39 offset:61440
	ds_read_b128 v[98:101], v39 offset:64000
	ds_read_b128 v[102:105], v32 offset:5120
	ds_read_b128 v[106:109], v32 offset:7680
	ds_read_b128 v[110:113], v33
	ds_read_b128 v[114:117], v33 offset:2560
	ds_read_b128 v[118:121], v33 offset:5120
	ds_read_b128 v[122:125], v33 offset:7680
	v_mfma_f32_16x16x32_bf16 v[126:129], v[222:225], v[206:209], v[126:129]
	v_mfma_f32_16x16x32_bf16 v[130:133], v[226:229], v[206:209], v[130:133]
	v_mfma_f32_16x16x32_bf16 v[134:137], v[230:233], v[206:209], v[134:137]
	v_mfma_f32_16x16x32_bf16 v[42:45], v[234:237], v[206:209], v[42:45]
	v_mfma_f32_16x16x32_bf16 v[58:61], v[222:225], v[210:213], v[58:61]
	v_mfma_f32_16x16x32_bf16 v[62:65], v[226:229], v[210:213], v[62:65]
	v_mfma_f32_16x16x32_bf16 v[74:77], v[230:233], v[210:213], v[74:77]
	v_mfma_f32_16x16x32_bf16 v[46:49], v[234:237], v[210:213], v[46:49]
	v_mfma_f32_16x16x32_bf16 v[66:69], v[222:225], v[214:217], v[66:69]
	v_mfma_f32_16x16x32_bf16 v[78:81], v[226:229], v[214:217], v[78:81]
	v_mfma_f32_16x16x32_bf16 v[82:85], v[230:233], v[214:217], v[82:85]
	v_mfma_f32_16x16x32_bf16 v[50:53], v[234:237], v[214:217], v[50:53]
	v_mfma_f32_16x16x32_bf16 v[70:73], v[222:225], v[218:221], v[70:73]
	v_mfma_f32_16x16x32_bf16 v[86:89], v[226:229], v[218:221], v[86:89]
	v_mfma_f32_16x16x32_bf16 v[90:93], v[230:233], v[218:221], v[90:93]
	v_mfma_f32_16x16x32_bf16 v[54:57], v[234:237], v[218:221], v[54:57]
	global_load_dwordx4 v[138:141], v[2:3], off offset:1920
	global_load_dwordx4 v[142:145], v[8:9], off offset:1920
	s_nop 0
	global_load_dwordx4 v[8:11], v[10:11], off offset:1920
	s_nop 0
	global_load_dwordx4 v[152:155], v[12:13], off offset:1920
	s_nop 0
	global_load_dwordx4 v[12:15], v[14:15], off offset:1920
	s_nop 0
	global_load_dwordx4 v[156:159], v[16:17], off offset:1920
	ds_read_b128 v[174:177], v30 offset:61504
	ds_read_b128 v[178:181], v30 offset:64064
	ds_read_b128 v[206:209], v34 offset:64
	ds_read_b128 v[210:213], v35 offset:64
	ds_read_b128 v[214:217], v41 offset:64
	ds_read_b128 v[218:221], v36 offset:64
	ds_read_b128 v[222:225], v37 offset:64
	ds_read_b128 v[226:229], v38 offset:64
	s_waitcnt lgkmcnt(11)
;     ...
;   for (int k0 = 0; k0 < K; k0 += 128) {
;     G_READ(fa1, fb1, 0, 32);
;     if (k0 + 128 < K) G_LOAD(ra0, rb0, k0 + 128);
;     __builtin_amdgcn_sched_barrier(0);
;     G_MFMA_ST(fa0, fb0, ra1, rb1, 1);
;     __syncthreads();
;     G_READ(fa0, fb0, 1, 0);
;     __builtin_amdgcn_sched_barrier(0);
;     G_MFMA(fa1, fb1);
;     __builtin_amdgcn_sched_barrier(0);
;     G_READ(fa1, fb1, 1, 32);
;     if (k0 + 192 < K) G_LOAD(ra1, rb1, k0 + 192);
;     __builtin_amdgcn_sched_barrier(0);
;     if (k0 + 128 < K) {
;       G_MFMA_ST(fa0, fb0, ra0, rb0, 0);
;       __syncthreads();
;       G_READ(fa0, fb0, 0, 0);
;     } else {
;       G_MFMA(fa0, fb0);
;     }
;     __builtin_amdgcn_sched_barrier(0);
;     G_MFMA(fa1, fb1);
;     __builtin_amdgcn_sched_barrier(0);
;   }
	v_mfma_f32_16x16x32_bf16 v[126:129], v[110:113], v[94:97], v[126:129]
	s_waitcnt vmcnt(11)
	ds_write_b128 v22, v[182:185]
	s_waitcnt vmcnt(7)
	ds_write_b128 v23, v[198:201]
	s_waitcnt lgkmcnt(12)
	v_mfma_f32_16x16x32_bf16 v[130:133], v[114:117], v[94:97], v[130:133]
	s_waitcnt lgkmcnt(11)
	v_mfma_f32_16x16x32_bf16 v[134:137], v[118:121], v[94:97], v[134:137]
	s_waitcnt lgkmcnt(10)
	v_mfma_f32_16x16x32_bf16 v[42:45], v[122:125], v[94:97], v[42:45]
	v_mfma_f32_16x16x32_bf16 v[58:61], v[110:113], v[98:101], v[58:61]
	ds_write_b128 v22, v[186:189] offset:10240
	s_waitcnt vmcnt(6)
	ds_write_b128 v25, v[202:205]
	v_mfma_f32_16x16x32_bf16 v[62:65], v[114:117], v[98:101], v[62:65]
	v_mfma_f32_16x16x32_bf16 v[74:77], v[118:121], v[98:101], v[74:77]
	v_mfma_f32_16x16x32_bf16 v[46:49], v[122:125], v[98:101], v[46:49]
	v_mfma_f32_16x16x32_bf16 v[66:69], v[110:113], v[102:105], v[66:69]
	ds_write_b128 v22, v[190:193] offset:20480
	v_mfma_f32_16x16x32_bf16 v[78:81], v[114:117], v[102:105], v[78:81]
	v_mfma_f32_16x16x32_bf16 v[82:85], v[118:121], v[102:105], v[82:85]
	v_mfma_f32_16x16x32_bf16 v[50:53], v[122:125], v[102:105], v[50:53]
	v_mfma_f32_16x16x32_bf16 v[70:73], v[110:113], v[106:109], v[70:73]
	ds_write_b128 v22, v[194:197] offset:30720
	v_mfma_f32_16x16x32_bf16 v[86:89], v[114:117], v[106:109], v[86:89]
	v_mfma_f32_16x16x32_bf16 v[90:93], v[118:121], v[106:109], v[90:93]
	v_mfma_f32_16x16x32_bf16 v[54:57], v[122:125], v[106:109], v[54:57]
	s_waitcnt lgkmcnt(0)
	s_barrier
	ds_read_b128 v[94:97], v39
	ds_read_b128 v[98:101], v39 offset:2560
	ds_read_b128 v[102:105], v39 offset:5120
	ds_read_b128 v[106:109], v39 offset:7680
	ds_read_b128 v[110:113], v40 offset:40960
	ds_read_b128 v[114:117], v40 offset:43520
	ds_read_b128 v[118:121], v40 offset:46080
	ds_read_b128 v[122:125], v40 offset:48640
	v_mfma_f32_16x16x32_bf16 v[126:129], v[214:217], v[174:177], v[126:129]
	v_mfma_f32_16x16x32_bf16 v[130:133], v[218:221], v[174:177], v[130:133]
	v_mfma_f32_16x16x32_bf16 v[134:137], v[222:225], v[174:177], v[134:137]
	v_mfma_f32_16x16x32_bf16 v[42:45], v[226:229], v[174:177], v[42:45]
	v_mfma_f32_16x16x32_bf16 v[58:61], v[214:217], v[178:181], v[58:61]
	v_mfma_f32_16x16x32_bf16 v[62:65], v[218:221], v[178:181], v[62:65]
	v_mfma_f32_16x16x32_bf16 v[74:77], v[222:225], v[178:181], v[74:77]
	v_mfma_f32_16x16x32_bf16 v[46:49], v[226:229], v[178:181], v[46:49]
	v_mfma_f32_16x16x32_bf16 v[66:69], v[214:217], v[206:209], v[66:69]
	v_mfma_f32_16x16x32_bf16 v[78:81], v[218:221], v[206:209], v[78:81]
	v_mfma_f32_16x16x32_bf16 v[82:85], v[222:225], v[206:209], v[82:85]
	v_mfma_f32_16x16x32_bf16 v[50:53], v[226:229], v[206:209], v[50:53]
	v_mfma_f32_16x16x32_bf16 v[70:73], v[214:217], v[210:213], v[70:73]
	v_mfma_f32_16x16x32_bf16 v[86:89], v[218:221], v[210:213], v[86:89]
	v_mfma_f32_16x16x32_bf16 v[90:93], v[222:225], v[210:213], v[90:93]
	v_mfma_f32_16x16x32_bf16 v[54:57], v[226:229], v[210:213], v[54:57]
	ds_read_b128 v[174:177], v30 offset:64
	ds_read_b128 v[178:181], v30 offset:2624
	ds_read_b128 v[182:185], v30 offset:5184
	ds_read_b128 v[186:189], v30 offset:7744
	ds_read_b128 v[190:193], v31 offset:41024
	ds_read_b128 v[194:197], v31 offset:43584
	ds_read_b128 v[198:201], v31 offset:46144
	ds_read_b128 v[202:205], v31 offset:48704
	s_waitcnt lgkmcnt(11)
	v_mfma_f32_16x16x32_bf16 v[126:129], v[110:113], v[94:97], v[126:129]
	s_waitcnt vmcnt(5)
	ds_write_b128 v22, v[138:141] offset:61440
	s_waitcnt vmcnt(1)
	ds_write_b128 v23, v[12:15] offset:61440
	s_waitcnt lgkmcnt(12)
	v_mfma_f32_16x16x32_bf16 v[130:133], v[114:117], v[94:97], v[130:133]
	s_waitcnt lgkmcnt(11)
	v_mfma_f32_16x16x32_bf16 v[134:137], v[118:121], v[94:97], v[134:137]
	s_waitcnt lgkmcnt(10)
	v_mfma_f32_16x16x32_bf16 v[12:15], v[122:125], v[94:97], v[42:45]
	v_mfma_f32_16x16x32_bf16 v[42:45], v[110:113], v[98:101], v[58:61]
	ds_write_b128 v24, v[142:145] offset:61440
	s_waitcnt vmcnt(0)
	ds_write_b128 v25, v[156:159] offset:61440
	v_mfma_f32_16x16x32_bf16 v[58:61], v[114:117], v[98:101], v[62:65]
	v_mfma_f32_16x16x32_bf16 v[62:65], v[118:121], v[98:101], v[74:77]
	v_mfma_f32_16x16x32_bf16 v[46:49], v[122:125], v[98:101], v[46:49]
	v_mfma_f32_16x16x32_bf16 v[66:69], v[110:113], v[102:105], v[66:69]
	ds_write_b128 v26, v[8:11] offset:61440
	v_mfma_f32_16x16x32_bf16 v[74:77], v[114:117], v[102:105], v[78:81]
	v_mfma_f32_16x16x32_bf16 v[78:81], v[118:121], v[102:105], v[82:85]
	v_mfma_f32_16x16x32_bf16 v[8:11], v[122:125], v[102:105], v[50:53]
	v_mfma_f32_16x16x32_bf16 v[50:53], v[110:113], v[106:109], v[70:73]
	ds_write_b128 v27, v[152:155] offset:61440
	v_mfma_f32_16x16x32_bf16 v[70:73], v[114:117], v[106:109], v[86:89]
	v_mfma_f32_16x16x32_bf16 v[82:85], v[118:121], v[106:109], v[90:93]
	v_mfma_f32_16x16x32_bf16 v[54:57], v[122:125], v[106:109], v[54:57]
	s_waitcnt lgkmcnt(0)
	s_barrier
;     ...
;     if (k0 + 128 < K) {
;       G_MFMA_ST(fa0, fb0, ra0, rb0, 0);
;       __syncthreads();
;       G_READ(fa0, fb0, 0, 0);
;     } else {
;       G_MFMA(fa0, fb0);
;     }
;     __builtin_amdgcn_sched_barrier(0);
;     G_MFMA(fa1, fb1);
;     __builtin_amdgcn_sched_barrier(0);
;   }
	ds_read_b128 v[86:89], v39 offset:61440
	ds_read_b128 v[90:93], v39 offset:64000
	ds_read_b128 v[94:97], v32 offset:5120
	ds_read_b128 v[98:101], v32 offset:7680
	ds_read_b128 v[102:105], v33
	ds_read_b128 v[106:109], v33 offset:2560
	ds_read_b128 v[110:113], v33 offset:5120
	ds_read_b128 v[114:117], v33 offset:7680
	v_mfma_f32_16x16x32_bf16 v[118:121], v[190:193], v[174:177], v[126:129]
	v_mfma_f32_16x16x32_bf16 v[122:125], v[194:197], v[174:177], v[130:133]
	v_mfma_f32_16x16x32_bf16 v[126:129], v[198:201], v[174:177], v[134:137]
	v_mfma_f32_16x16x32_bf16 v[12:15], v[202:205], v[174:177], v[12:15]
	v_mfma_f32_16x16x32_bf16 v[42:45], v[190:193], v[178:181], v[42:45]
	v_mfma_f32_16x16x32_bf16 v[58:61], v[194:197], v[178:181], v[58:61]
	v_mfma_f32_16x16x32_bf16 v[62:65], v[198:201], v[178:181], v[62:65]
	v_mfma_f32_16x16x32_bf16 v[46:49], v[202:205], v[178:181], v[46:49]
	v_mfma_f32_16x16x32_bf16 v[66:69], v[190:193], v[182:185], v[66:69]
	v_mfma_f32_16x16x32_bf16 v[74:77], v[194:197], v[182:185], v[74:77]
	v_mfma_f32_16x16x32_bf16 v[78:81], v[198:201], v[182:185], v[78:81]
	v_mfma_f32_16x16x32_bf16 v[8:11], v[202:205], v[182:185], v[8:11]
	v_mfma_f32_16x16x32_bf16 v[50:53], v[190:193], v[186:189], v[50:53]
	v_mfma_f32_16x16x32_bf16 v[70:73], v[194:197], v[186:189], v[70:73]
	v_mfma_f32_16x16x32_bf16 v[82:85], v[198:201], v[186:189], v[82:85]
	v_mfma_f32_16x16x32_bf16 v[54:57], v[202:205], v[186:189], v[54:57]
	ds_read_b128 v[130:133], v30 offset:61504
	ds_read_b128 v[134:137], v30 offset:64064
	ds_read_b128 v[138:141], v34 offset:64
	ds_read_b128 v[142:145], v35 offset:64
	ds_read_b128 v[152:155], v41 offset:64
	ds_read_b128 v[156:159], v36 offset:64
	ds_read_b128 v[174:177], v37 offset:64
	ds_read_b128 v[178:181], v38 offset:64
	s_waitcnt lgkmcnt(11)
	v_mfma_f32_16x16x32_bf16 v[118:121], v[102:105], v[86:89], v[118:121]
	s_waitcnt lgkmcnt(10)
	v_mfma_f32_16x16x32_bf16 v[122:125], v[106:109], v[86:89], v[122:125]
	s_waitcnt lgkmcnt(9)
	v_mfma_f32_16x16x32_bf16 v[126:129], v[110:113], v[86:89], v[126:129]
	s_waitcnt lgkmcnt(8)
	v_mfma_f32_16x16x32_bf16 v[12:15], v[114:117], v[86:89], v[12:15]
	v_mfma_f32_16x16x32_bf16 v[40:43], v[102:105], v[90:93], v[42:45]
	v_mfma_f32_16x16x32_bf16 v[58:61], v[106:109], v[90:93], v[58:61]
	v_mfma_f32_16x16x32_bf16 v[62:65], v[110:113], v[90:93], v[62:65]
	v_mfma_f32_16x16x32_bf16 v[44:47], v[114:117], v[90:93], v[46:49]
	v_mfma_f32_16x16x32_bf16 v[66:69], v[102:105], v[94:97], v[66:69]
	v_mfma_f32_16x16x32_bf16 v[74:77], v[106:109], v[94:97], v[74:77]
	v_mfma_f32_16x16x32_bf16 v[78:81], v[110:113], v[94:97], v[78:81]
	v_mfma_f32_16x16x32_bf16 v[8:11], v[114:117], v[94:97], v[8:11]
	v_mfma_f32_16x16x32_bf16 v[48:51], v[102:105], v[98:101], v[50:53]
	v_mfma_f32_16x16x32_bf16 v[70:73], v[106:109], v[98:101], v[70:73]
	v_mfma_f32_16x16x32_bf16 v[82:85], v[110:113], v[98:101], v[82:85]
	v_mfma_f32_16x16x32_bf16 v[52:55], v[114:117], v[98:101], v[54:57]
	s_waitcnt lgkmcnt(3)
	v_mfma_f32_16x16x32_bf16 v[86:89], v[152:155], v[130:133], v[118:121]
	s_waitcnt lgkmcnt(2)
	v_mfma_f32_16x16x32_bf16 v[90:93], v[156:159], v[130:133], v[122:125]
	s_waitcnt lgkmcnt(1)
	v_mfma_f32_16x16x32_bf16 v[94:97], v[174:177], v[130:133], v[126:129]
	s_waitcnt lgkmcnt(0)
;     ...
;     G_MFMA(fa1, fb1);
;     __builtin_amdgcn_sched_barrier(0);
;   }
; template <int TN, bool NTS = false>
; __device__ __forceinline__ void store_tile_bf16(const f32x4 (&acc)[4][TN], bf16_t* __restrict__ dst, int ldd, bf16_t* sT,
;                                                 const int tidx) {
;   constexpr int BN = 32 * TN, TS = BN + 8, CPR = BN / 8;
;   const int lane = tidx & 63, w = tidx >> 6;
;   const int wm = w >> 1, wn = w & 1, l15 = lane & 15, quad = lane >> 4;
;   __syncthreads();
; #pragma unroll
;   for (int i = 0; i < 4; i++)
; #pragma unroll
;     for (int j = 0; j < TN; j++)
; #pragma unroll
;       for (int r = 0; r < 4; r++)
;         sT[(wm * 64 + i * 16 + quad * 4 + r) * TS + wn * TN * 16 + j * 16 + l15] = f2bf(acc[i][j][r]);
;   __syncthreads();
; #pragma unroll
;   for (int c = tidx; c < 256 * CPR; c += NT) {
;     int row = c / CPR, cc = c % CPR;
;     const u32x4 v_ = *(const u32x4*)(sT + row * TS + cc * 8);
;     if (NTS) __builtin_nontemporal_store(v_, (u32x4*)(dst + (size_t)row * ldd + cc * 8));
;     else *(u32x4*)(dst + (size_t)row * ldd + cc * 8) = v_;
;   }
	v_mfma_f32_16x16x32_bf16 v[12:15], v[178:181], v[130:133], v[12:15]
	v_mfma_f32_16x16x32_bf16 v[40:43], v[152:155], v[134:137], v[40:43]
	v_mfma_f32_16x16x32_bf16 v[56:59], v[156:159], v[134:137], v[58:61]
	v_mfma_f32_16x16x32_bf16 v[60:63], v[174:177], v[134:137], v[62:65]
	v_mfma_f32_16x16x32_bf16 v[44:47], v[178:181], v[134:137], v[44:47]
	v_mfma_f32_16x16x32_bf16 v[64:67], v[152:155], v[138:141], v[66:69]
	v_mfma_f32_16x16x32_bf16 v[74:77], v[156:159], v[138:141], v[74:77]
	v_mfma_f32_16x16x32_bf16 v[78:81], v[174:177], v[138:141], v[78:81]
	v_mfma_f32_16x16x32_bf16 v[8:11], v[178:181], v[138:141], v[8:11]
	v_mfma_f32_16x16x32_bf16 v[48:51], v[152:155], v[142:145], v[48:51]
	v_mfma_f32_16x16x32_bf16 v[68:71], v[156:159], v[142:145], v[70:73]
	v_mfma_f32_16x16x32_bf16 v[82:85], v[174:177], v[142:145], v[82:85]
	v_mfma_f32_16x16x32_bf16 v[52:55], v[178:181], v[142:145], v[52:55]
	s_mul_hi_i32 s13, s14, 0x3a0000
	s_mul_i32 s14, s14, 0x3a0000
	s_add_u32 s14, s94, s14
	s_addc_u32 s15, s95, s13
	s_lshl_b32 s12, s12, 8
	s_add_u32 s12, s14, s12
	s_addc_u32 s13, s15, 0
	v_lshrrev_b32_e32 v2, 7, v150
	v_and_b32_e32 v3, 7, v150
	v_lshl_or_b32 v2, v2, 6, v3
	v_mul_u32_u24_e32 v2, 0x3a00, v2
	v_bfe_u32 v3, v150, 6, 1
	v_bfe_u32 v16, v150, 3, 1
	v_lshl_or_b32 v3, v3, 1, v16
	v_bfe_u32 v16, v150, 4, 2
	v_lshl_or_b32 v3, v3, 2, v16
	v_lshl_add_u32 v2, v3, 4, v2
	v_add_u32_e32 v3, 0x1d000, v2
	v_cvt_pk_bf16_f32 v86, v86, v87
	v_cvt_pk_bf16_f32 v87, v88, v89
	v_cvt_pk_bf16_f32 v88, v90, v91
	v_cvt_pk_bf16_f32 v89, v92, v93
	v_cvt_pk_bf16_f32 v94, v94, v95
	v_cvt_pk_bf16_f32 v95, v96, v97
	v_cvt_pk_bf16_f32 v96, v12, v13
	v_cvt_pk_bf16_f32 v97, v14, v15
	v_mov_b32_e32 v90, v86
	v_mov_b32_e32 v91, v87
	v_mov_b32_e32 v92, v88
	v_mov_b32_e32 v93, v89
	v_mov_b32_dpp v86, v94 row_ror:8 row_mask:0xf bank_mask:0xc
	v_mov_b32_dpp v87, v95 row_ror:8 row_mask:0xf bank_mask:0xc
	v_mov_b32_dpp v88, v96 row_ror:8 row_mask:0xf bank_mask:0xc
	v_mov_b32_dpp v89, v97 row_ror:8 row_mask:0xf bank_mask:0xc
	v_mov_b32_dpp v94, v90 row_ror:8 row_mask:0xf bank_mask:0x3
	v_mov_b32_dpp v95, v91 row_ror:8 row_mask:0xf bank_mask:0x3
	v_mov_b32_dpp v96, v92 row_ror:8 row_mask:0xf bank_mask:0x3
	v_mov_b32_dpp v97, v93 row_ror:8 row_mask:0xf bank_mask:0x3
	global_store_dwordx4 v2, v[86:89], s[12:13] nt
	global_store_dwordx4 v3, v[94:97], s[12:13] nt
	s_add_u32 s12, s12, 0x3a000
	s_addc_u32 s13, s13, 0
	v_cvt_pk_bf16_f32 v40, v40, v41
	v_cvt_pk_bf16_f32 v41, v42, v43
	v_cvt_pk_bf16_f32 v42, v56, v57
	v_cvt_pk_bf16_f32 v43, v58, v59
	v_cvt_pk_bf16_f32 v60, v60, v61
	v_cvt_pk_bf16_f32 v61, v62, v63
	v_cvt_pk_bf16_f32 v62, v44, v45
	v_cvt_pk_bf16_f32 v63, v46, v47
	v_mov_b32_e32 v56, v40
	v_mov_b32_e32 v57, v41
	v_mov_b32_e32 v58, v42
	v_mov_b32_e32 v59, v43
	v_mov_b32_dpp v40, v60 row_ror:8 row_mask:0xf bank_mask:0xc
	v_mov_b32_dpp v41, v61 row_ror:8 row_mask:0xf bank_mask:0xc
	v_mov_b32_dpp v42, v62 row_ror:8 row_mask:0xf bank_mask:0xc
	v_mov_b32_dpp v43, v63 row_ror:8 row_mask:0xf bank_mask:0xc
	v_mov_b32_dpp v60, v56 row_ror:8 row_mask:0xf bank_mask:0x3
	v_mov_b32_dpp v61, v57 row_ror:8 row_mask:0xf bank_mask:0x3
	v_mov_b32_dpp v62, v58 row_ror:8 row_mask:0xf bank_mask:0x3
	v_mov_b32_dpp v63, v59 row_ror:8 row_mask:0xf bank_mask:0x3
	global_store_dwordx4 v2, v[40:43], s[12:13] nt
	global_store_dwordx4 v3, v[60:63], s[12:13] nt
	s_add_u32 s12, s12, 0x3a000
	s_addc_u32 s13, s13, 0
	v_cvt_pk_bf16_f32 v64, v64, v65
	v_cvt_pk_bf16_f32 v65, v66, v67
	v_cvt_pk_bf16_f32 v66, v74, v75
	v_cvt_pk_bf16_f32 v67, v76, v77
	v_cvt_pk_bf16_f32 v78, v78, v79
	v_cvt_pk_bf16_f32 v79, v80, v81
	v_cvt_pk_bf16_f32 v80, v8, v9
	v_cvt_pk_bf16_f32 v81, v10, v11
	v_mov_b32_e32 v74, v64
	v_mov_b32_e32 v75, v65
	v_mov_b32_e32 v76, v66
	v_mov_b32_e32 v77, v67
	v_mov_b32_dpp v64, v78 row_ror:8 row_mask:0xf bank_mask:0xc
	v_mov_b32_dpp v65, v79 row_ror:8 row_mask:0xf bank_mask:0xc
	v_mov_b32_dpp v66, v80 row_ror:8 row_mask:0xf bank_mask:0xc
	v_mov_b32_dpp v67, v81 row_ror:8 row_mask:0xf bank_mask:0xc
	v_mov_b32_dpp v78, v74 row_ror:8 row_mask:0xf bank_mask:0x3
	v_mov_b32_dpp v79, v75 row_ror:8 row_mask:0xf bank_mask:0x3
	v_mov_b32_dpp v80, v76 row_ror:8 row_mask:0xf bank_mask:0x3
	v_mov_b32_dpp v81, v77 row_ror:8 row_mask:0xf bank_mask:0x3
	global_store_dwordx4 v2, v[64:67], s[12:13] nt
	global_store_dwordx4 v3, v[78:81], s[12:13] nt
	s_add_u32 s12, s12, 0x3a000
	s_addc_u32 s13, s13, 0
	v_cvt_pk_bf16_f32 v48, v48, v49
	v_cvt_pk_bf16_f32 v49, v50, v51
	v_cvt_pk_bf16_f32 v50, v68, v69
	v_cvt_pk_bf16_f32 v51, v70, v71
	v_cvt_pk_bf16_f32 v82, v82, v83
	v_cvt_pk_bf16_f32 v83, v84, v85
	v_cvt_pk_bf16_f32 v84, v52, v53
	v_cvt_pk_bf16_f32 v85, v54, v55
	v_mov_b32_e32 v68, v48
	v_mov_b32_e32 v69, v49
	v_mov_b32_e32 v70, v50
	v_mov_b32_e32 v71, v51
	v_mov_b32_dpp v48, v82 row_ror:8 row_mask:0xf bank_mask:0xc
	v_mov_b32_dpp v49, v83 row_ror:8 row_mask:0xf bank_mask:0xc
	v_mov_b32_dpp v50, v84 row_ror:8 row_mask:0xf bank_mask:0xc
	v_mov_b32_dpp v51, v85 row_ror:8 row_mask:0xf bank_mask:0xc
	v_mov_b32_dpp v82, v68 row_ror:8 row_mask:0xf bank_mask:0x3
	v_mov_b32_dpp v83, v69 row_ror:8 row_mask:0xf bank_mask:0x3
	v_mov_b32_dpp v84, v70 row_ror:8 row_mask:0xf bank_mask:0x3
	v_mov_b32_dpp v85, v71 row_ror:8 row_mask:0xf bank_mask:0x3
	global_store_dwordx4 v2, v[48:51], s[12:13] nt
	global_store_dwordx4 v3, v[82:85], s[12:13] nt
	s_branch .LBB0_581
